# pipelined loads in sample-row small GEMMs and sample cross-attn, p2 wait placement, barrier acquire-invalidate issued with arrive
# speedup vs baseline: 1.0179x; 1.0179x over previous
; __device__ __forceinline__ unsigned xb_add(unsigned* p, unsigned v) { return __hip_atomic_fetch_add(p, v, __ATOMIC_RELAXED, __HIP_MEMORY_SCOPE_AGENT); }
; __device__ __forceinline__ void xcd_barrier(const XcdBarrier& b) {
;     ...
;             __builtin_amdgcn_fence(__ATOMIC_ACQUIRE, "agent");
;             xb_add(&bar[XB_XGEN(bx_)], 1u);
;             asm volatile("s_waitcnt vmcnt(0)" ::: "memory");
.LBB0_276:
	s_or_b64 exec, exec, s[0:1]
	s_add_i32 s62, s20, 0x900
	s_lshl_b64 s[0:1], s[62:63], 2
	s_add_u32 s0, s34, s0
	s_addc_u32 s1, s35, s1
	v_mov_b64_e32 v[2:3], s[0:1]
	v_mov_b32_e32 v0, 1
	s_waitcnt vmcnt(0) lgkmcnt(0)
	flat_atomic_add v[2:3], v0
	s_waitcnt vmcnt(0)

; #define LAS __attribute__((address_space(3)))
; __device__ __forceinline__ void small_gemm_q256(LAS unsigned char* lds, const bf16_t* A, const bf16_t* Bt, int unit, const float* SS, float sc, bf16_t* OUT) {
;     int tid = threadIdx.x; asm volatile("" : "+v"(tid));
;     const int wave = __builtin_amdgcn_readfirstlane(tid >> 6), lane = tid & 63, li = lane & 15, g4 = lane >> 4;
;     const int rt = unit >> 2, ct = unit & 3, row0 = TP + 16 * rt, col0 = 256 * ct;
;     constexpr int K = D, KS = 4;
;     const int row = tid >> 5;
;     f32x4 sv[4];
; #pragma unroll
;     for (int q = 0; q < 4; ++q) sv[q] = ((const f32x4*)(SS + (size_t)(row0 + row) * 16))[q];
;     f32x4 acc[16];
; #pragma unroll
;     for (int t = 0; t < 16; ++t) acc[t] = (f32x4){0.f, 0.f, 0.f, 0.f};
;     const bf16_t* ap = A + (size_t)(row0 + li) * K + 8 * g4 + 32 * wave * KS;
;     const bf16_t* bp = Bt + (size_t)(col0 + li) * K + 8 * g4 + 32 * wave * KS;
; #pragma unroll 2
;     for (int ks = 0; ks < KS; ++ks) {
;         const bf16x8 a = *(const bf16x8*)(ap + 32 * ks);
; #pragma unroll
;         for (int t = 0; t < 16; ++t) { const bf16x8 b = *(const bf16x8*)(bp + (size_t)16 * t * K + 32 * ks); acc[t] = __builtin_amdgcn_mfma_f32_16x16x32_bf16(b, a, acc[t], 0, 0, 0); }
.LBB0_586:
	v_mov_b32_e32 v112, v208
	s_and_b32 s4, s12, -16
	v_readfirstlane_b32 s0, v112
	s_ashr_i32 s3, s0, 6
	s_lshl_b32 s0, s14, 2
	s_and_b32 s0, s0, -16
	s_addk_i32 s0, 0x4000
	v_ashrrev_i32_e32 v113, 5, v112
	v_add_u32_e32 v82, s0, v113
	v_ashrrev_i32_e32 v83, 31, v82
	v_lshlrev_b64 v[2:3], 6, v[82:83]
	v_lshl_add_u64 v[2:3], s[10:11], 0, v[2:3]
	global_load_dwordx4 v[14:17], v[2:3], off
	global_load_dwordx4 v[10:13], v[2:3], off offset:16
	global_load_dwordx4 v[6:9], v[2:3], off offset:32
	s_nop 0
	global_load_dwordx4 v[2:5], v[2:3], off offset:48
	v_and_b32_e32 v0, 15, v112
	s_lshl_b32 s0, s3, 7
	s_addk_i32 s4, 0x4000
	s_ashr_i32 s1, s0, 31
	v_or_b32_e32 v18, s4, v0
	s_lshr_b32 s2, s13, 8
	v_ashrrev_i32_e32 v19, 31, v18
	s_lshl_b64 s[0:1], s[0:1], 1
	v_lshlrev_b64 v[18:19], 11, v[18:19]
	v_and_b32_e32 v20, 48, v112
	s_add_u32 s4, s22, s0
	v_or_b32_e32 v18, v18, v20
	s_addc_u32 s5, s23, s1
	v_lshl_add_u64 v[84:85], s[4:5], 0, v[18:19]
	v_or_b32_e32 v18, s0, v20
	s_lshl_b32 s0, s13, 11
	s_and_b32 s0, s0, 0x180000
	v_mov_b32_e32 v19, s1
	v_lshlrev_b32_e32 v115, 10, v0
	v_lshl_or_b32 v0, v0, 11, s0
	v_lshl_add_u64 v[18:19], v[18:19], 0, v[0:1]
	v_lshl_add_u64 v[86:87], s[20:21], 0, v[18:19]
	v_mov_b32_e32 v18, 0
	s_mov_b32 s19, s47
	s_mov_b32 s18, s45
	v_lshrrev_b32_e32 v114, 4, v112
	s_mov_b64 s[0:1], 0
	v_mov_b32_e32 v19, v18
	v_mov_b32_e32 v20, v18
	v_mov_b32_e32 v21, v18
	v_mov_b32_e32 v22, v18
	v_mov_b32_e32 v23, v18
	v_mov_b32_e32 v24, v18
	v_mov_b32_e32 v25, v18
	v_mov_b32_e32 v26, v18
	v_mov_b32_e32 v27, v18
	v_mov_b32_e32 v28, v18
	v_mov_b32_e32 v29, v18
	v_mov_b32_e32 v30, v18
	v_mov_b32_e32 v31, v18
	v_mov_b32_e32 v32, v18
	v_mov_b32_e32 v33, v18
	v_mov_b32_e32 v34, v18
	v_mov_b32_e32 v35, v18
	v_mov_b32_e32 v36, v18
	v_mov_b32_e32 v37, v18
	v_mov_b32_e32 v38, v18
	v_mov_b32_e32 v39, v18
	v_mov_b32_e32 v40, v18
	v_mov_b32_e32 v41, v18
	v_mov_b32_e32 v42, v18
	v_mov_b32_e32 v43, v18
	v_mov_b32_e32 v44, v18
	v_mov_b32_e32 v45, v18
	v_mov_b32_e32 v50, v18
	v_mov_b32_e32 v51, v18
	v_mov_b32_e32 v52, v18
	v_mov_b32_e32 v53, v18
	v_mov_b32_e32 v54, v18
	v_mov_b32_e32 v55, v18
	v_mov_b32_e32 v56, v18
	v_mov_b32_e32 v57, v18
	v_mov_b32_e32 v58, v18
	v_mov_b32_e32 v59, v18
	v_mov_b32_e32 v60, v18
	v_mov_b32_e32 v61, v18
	v_mov_b32_e32 v62, v18
	v_mov_b32_e32 v63, v18
	v_mov_b32_e32 v64, v18
	v_mov_b32_e32 v65, v18
	v_mov_b32_e32 v66, v18
	v_mov_b32_e32 v67, v18
	v_mov_b32_e32 v68, v18
	v_mov_b32_e32 v69, v18
	v_mov_b32_e32 v70, v18
	v_mov_b32_e32 v71, v18
	v_mov_b32_e32 v72, v18
	v_mov_b32_e32 v73, v18
	v_mov_b32_e32 v74, v18
	v_mov_b32_e32 v75, v18
	v_mov_b32_e32 v76, v18
	v_mov_b32_e32 v77, v18
	v_mov_b32_e32 v78, v18
	v_mov_b32_e32 v79, v18
	v_mov_b32_e32 v80, v18
	v_mov_b32_e32 v81, v18
	v_mov_b32_e32 v46, v18
	v_mov_b32_e32 v47, v18
	v_mov_b32_e32 v48, v18
	v_mov_b32_e32 v49, v18
	s_mov_b64 s[0:1], 0x8000
	global_load_dwordx4 v[88:91], v[84:85], off
	global_load_dwordx4 v[92:95], v[86:87], off
	v_lshl_add_u64 v[144:145], v[86:87], 0, s[0:1]
	global_load_dwordx4 v[96:99], v[144:145], off
	v_lshl_add_u64 v[146:147], v[144:145], 0, s[0:1]
	global_load_dwordx4 v[100:103], v[146:147], off
	v_lshl_add_u64 v[144:145], v[146:147], 0, s[0:1]
	global_load_dwordx4 v[104:107], v[144:145], off
	v_lshl_add_u64 v[146:147], v[144:145], 0, s[0:1]
	global_load_dwordx4 v[108:111], v[146:147], off
	v_lshl_add_u64 v[144:145], v[146:147], 0, s[0:1]
	global_load_dwordx4 v[116:119], v[144:145], off
	v_lshl_add_u64 v[146:147], v[144:145], 0, s[0:1]
	global_load_dwordx4 v[120:123], v[146:147], off
	v_lshl_add_u64 v[144:145], v[146:147], 0, s[0:1]
	global_load_dwordx4 v[124:127], v[144:145], off
	v_lshl_add_u64 v[146:147], v[144:145], 0, s[0:1]
	global_load_dwordx4 v[128:131], v[146:147], off
	v_lshl_add_u64 v[144:145], v[146:147], 0, s[0:1]
	global_load_dwordx4 v[132:135], v[144:145], off
	v_lshl_add_u64 v[146:147], v[144:145], 0, s[0:1]
	global_load_dwordx4 v[136:139], v[146:147], off
	v_lshl_add_u64 v[144:145], v[146:147], 0, s[0:1]
	global_load_dwordx4 v[140:143], v[144:145], off
	s_waitcnt vmcnt(11)
	v_mfma_f32_16x16x32_bf16 v[46:49], v[92:95], v[88:91], v[46:49]
	v_lshl_add_u64 v[146:147], v[144:145], 0, s[0:1]
	global_load_dwordx4 v[92:95], v[146:147], off
	s_waitcnt vmcnt(11)
	v_mfma_f32_16x16x32_bf16 v[78:81], v[96:99], v[88:91], v[78:81]
	v_lshl_add_u64 v[144:145], v[146:147], 0, s[0:1]
	global_load_dwordx4 v[96:99], v[144:145], off
	s_waitcnt vmcnt(11)
	v_mfma_f32_16x16x32_bf16 v[74:77], v[100:103], v[88:91], v[74:77]
	v_lshl_add_u64 v[146:147], v[144:145], 0, s[0:1]
	global_load_dwordx4 v[100:103], v[146:147], off
	s_waitcnt vmcnt(11)
	v_mfma_f32_16x16x32_bf16 v[70:73], v[104:107], v[88:91], v[70:73]
	v_lshl_add_u64 v[144:145], v[146:147], 0, s[0:1]
	global_load_dwordx4 v[104:107], v[144:145], off
	s_waitcnt vmcnt(11)
	v_mfma_f32_16x16x32_bf16 v[66:69], v[108:111], v[88:91], v[66:69]
	global_load_dwordx4 v[108:111], v[84:85], off offset:64
	s_waitcnt vmcnt(11)
	v_mfma_f32_16x16x32_bf16 v[62:65], v[116:119], v[88:91], v[62:65]
	global_load_dwordx4 v[116:119], v[86:87], off offset:64
	s_waitcnt vmcnt(11)
	v_mfma_f32_16x16x32_bf16 v[58:61], v[120:123], v[88:91], v[58:61]
	v_lshl_add_u64 v[144:145], v[86:87], 0, s[0:1]
	global_load_dwordx4 v[120:123], v[144:145], off offset:64
	s_waitcnt vmcnt(11)
	v_mfma_f32_16x16x32_bf16 v[54:57], v[124:127], v[88:91], v[54:57]
	v_lshl_add_u64 v[146:147], v[144:145], 0, s[0:1]
	global_load_dwordx4 v[124:127], v[146:147], off offset:64
	s_waitcnt vmcnt(11)
	v_mfma_f32_16x16x32_bf16 v[50:53], v[128:131], v[88:91], v[50:53]
	v_lshl_add_u64 v[144:145], v[146:147], 0, s[0:1]
	global_load_dwordx4 v[128:131], v[144:145], off offset:64
	s_waitcnt vmcnt(11)
; __device__ __forceinline__ void small_gemm_q256(LAS unsigned char* lds, const bf16_t* A, const bf16_t* Bt, int unit, const float* SS, float sc, bf16_t* OUT) {
;     ...
; #pragma unroll 2
;     for (int ks = 0; ks < KS; ++ks) {
;         const bf16x8 a = *(const bf16x8*)(ap + 32 * ks);
; #pragma unroll
;         for (int t = 0; t < 16; ++t) { const bf16x8 b = *(const bf16x8*)(bp + (size_t)16 * t * K + 32 * ks); acc[t] = __builtin_amdgcn_mfma_f32_16x16x32_bf16(b, a, acc[t], 0, 0, 0); }
	v_mfma_f32_16x16x32_bf16 v[42:45], v[132:135], v[88:91], v[42:45]
	v_lshl_add_u64 v[146:147], v[144:145], 0, s[0:1]
	global_load_dwordx4 v[132:135], v[146:147], off offset:64
	s_waitcnt vmcnt(11)
	v_mfma_f32_16x16x32_bf16 v[38:41], v[136:139], v[88:91], v[38:41]
	v_lshl_add_u64 v[144:145], v[146:147], 0, s[0:1]
	global_load_dwordx4 v[136:139], v[144:145], off offset:64
	s_waitcnt vmcnt(11)
	v_mfma_f32_16x16x32_bf16 v[34:37], v[140:143], v[88:91], v[34:37]
	v_lshl_add_u64 v[146:147], v[144:145], 0, s[0:1]
	global_load_dwordx4 v[140:143], v[146:147], off offset:64
	s_waitcnt vmcnt(11)
	v_mfma_f32_16x16x32_bf16 v[30:33], v[92:95], v[88:91], v[30:33]
	v_lshl_add_u64 v[144:145], v[146:147], 0, s[0:1]
	global_load_dwordx4 v[92:95], v[144:145], off offset:64
	s_waitcnt vmcnt(11)
	v_mfma_f32_16x16x32_bf16 v[26:29], v[96:99], v[88:91], v[26:29]
	v_lshl_add_u64 v[146:147], v[144:145], 0, s[0:1]
	global_load_dwordx4 v[96:99], v[146:147], off offset:64
	s_waitcnt vmcnt(11)
	v_mfma_f32_16x16x32_bf16 v[22:25], v[100:103], v[88:91], v[22:25]
	v_lshl_add_u64 v[144:145], v[146:147], 0, s[0:1]
	global_load_dwordx4 v[100:103], v[144:145], off offset:64
	s_waitcnt vmcnt(11)
	v_mfma_f32_16x16x32_bf16 v[18:21], v[104:107], v[88:91], v[18:21]
	v_lshl_add_u64 v[146:147], v[144:145], 0, s[0:1]
	global_load_dwordx4 v[104:107], v[146:147], off offset:64
	v_lshl_add_u64 v[144:145], v[146:147], 0, s[0:1]
	global_load_dwordx4 v[88:91], v[144:145], off offset:64
	s_waitcnt vmcnt(11)
	v_mfma_f32_16x16x32_bf16 v[46:49], v[116:119], v[108:111], v[46:49]
	v_lshl_add_u64 v[146:147], v[144:145], 0, s[0:1]
	global_load_dwordx4 v[116:119], v[146:147], off offset:64
	s_waitcnt vmcnt(11)
	v_mfma_f32_16x16x32_bf16 v[78:81], v[120:123], v[108:111], v[78:81]
	v_lshl_add_u64 v[144:145], v[146:147], 0, s[0:1]
	global_load_dwordx4 v[120:123], v[144:145], off offset:64
	s_waitcnt vmcnt(11)
	v_mfma_f32_16x16x32_bf16 v[74:77], v[124:127], v[108:111], v[74:77]
	v_lshl_add_u64 v[146:147], v[144:145], 0, s[0:1]
	global_load_dwordx4 v[124:127], v[146:147], off offset:64
	s_waitcnt vmcnt(11)
	v_mfma_f32_16x16x32_bf16 v[70:73], v[128:131], v[108:111], v[70:73]
	v_lshl_add_u64 v[144:145], v[146:147], 0, s[0:1]
	global_load_dwordx4 v[128:131], v[144:145], off offset:64
	s_waitcnt vmcnt(11)
	v_mfma_f32_16x16x32_bf16 v[66:69], v[132:135], v[108:111], v[66:69]
	global_load_dwordx4 v[132:135], v[84:85], off offset:128
	s_waitcnt vmcnt(11)
	v_mfma_f32_16x16x32_bf16 v[62:65], v[136:139], v[108:111], v[62:65]
	global_load_dwordx4 v[136:139], v[86:87], off offset:128
	s_waitcnt vmcnt(11)
	v_mfma_f32_16x16x32_bf16 v[58:61], v[140:143], v[108:111], v[58:61]
	v_lshl_add_u64 v[144:145], v[86:87], 0, s[0:1]
	global_load_dwordx4 v[140:143], v[144:145], off offset:128
	s_waitcnt vmcnt(11)
	v_mfma_f32_16x16x32_bf16 v[54:57], v[92:95], v[108:111], v[54:57]
	v_lshl_add_u64 v[146:147], v[144:145], 0, s[0:1]
	global_load_dwordx4 v[92:95], v[146:147], off offset:128
	s_waitcnt vmcnt(11)
	v_mfma_f32_16x16x32_bf16 v[50:53], v[96:99], v[108:111], v[50:53]
	v_lshl_add_u64 v[144:145], v[146:147], 0, s[0:1]
	global_load_dwordx4 v[96:99], v[144:145], off offset:128
	s_waitcnt vmcnt(11)
	v_mfma_f32_16x16x32_bf16 v[42:45], v[100:103], v[108:111], v[42:45]
	v_lshl_add_u64 v[146:147], v[144:145], 0, s[0:1]
	global_load_dwordx4 v[100:103], v[146:147], off offset:128
	s_waitcnt vmcnt(11)
	v_mfma_f32_16x16x32_bf16 v[38:41], v[104:107], v[108:111], v[38:41]
	v_lshl_add_u64 v[144:145], v[146:147], 0, s[0:1]
	global_load_dwordx4 v[104:107], v[144:145], off offset:128
	s_waitcnt vmcnt(11)
	v_mfma_f32_16x16x32_bf16 v[34:37], v[88:91], v[108:111], v[34:37]
	v_lshl_add_u64 v[146:147], v[144:145], 0, s[0:1]
	global_load_dwordx4 v[88:91], v[146:147], off offset:128
	s_waitcnt vmcnt(11)
	v_mfma_f32_16x16x32_bf16 v[30:33], v[116:119], v[108:111], v[30:33]
	v_lshl_add_u64 v[144:145], v[146:147], 0, s[0:1]
	global_load_dwordx4 v[116:119], v[144:145], off offset:128
	s_waitcnt vmcnt(11)
	v_mfma_f32_16x16x32_bf16 v[26:29], v[120:123], v[108:111], v[26:29]
	v_lshl_add_u64 v[146:147], v[144:145], 0, s[0:1]
	global_load_dwordx4 v[120:123], v[146:147], off offset:128
	s_waitcnt vmcnt(11)
	v_mfma_f32_16x16x32_bf16 v[22:25], v[124:127], v[108:111], v[22:25]
	v_lshl_add_u64 v[144:145], v[146:147], 0, s[0:1]
	global_load_dwordx4 v[124:127], v[144:145], off offset:128
	s_waitcnt vmcnt(11)
	v_mfma_f32_16x16x32_bf16 v[18:21], v[128:131], v[108:111], v[18:21]
	v_lshl_add_u64 v[146:147], v[144:145], 0, s[0:1]
	global_load_dwordx4 v[128:131], v[146:147], off offset:128
	v_lshl_add_u64 v[144:145], v[146:147], 0, s[0:1]
	global_load_dwordx4 v[108:111], v[144:145], off offset:128
	s_waitcnt vmcnt(11)
	v_mfma_f32_16x16x32_bf16 v[46:49], v[136:139], v[132:135], v[46:49]
	v_lshl_add_u64 v[146:147], v[144:145], 0, s[0:1]
	global_load_dwordx4 v[136:139], v[146:147], off offset:128
	s_waitcnt vmcnt(11)
	v_mfma_f32_16x16x32_bf16 v[78:81], v[140:143], v[132:135], v[78:81]
	v_lshl_add_u64 v[144:145], v[146:147], 0, s[0:1]
	global_load_dwordx4 v[140:143], v[144:145], off offset:128
	s_waitcnt vmcnt(11)
	v_mfma_f32_16x16x32_bf16 v[74:77], v[92:95], v[132:135], v[74:77]
	v_lshl_add_u64 v[146:147], v[144:145], 0, s[0:1]
	global_load_dwordx4 v[92:95], v[146:147], off offset:128
	s_waitcnt vmcnt(11)
	v_mfma_f32_16x16x32_bf16 v[70:73], v[96:99], v[132:135], v[70:73]
	v_lshl_add_u64 v[144:145], v[146:147], 0, s[0:1]
	global_load_dwordx4 v[96:99], v[144:145], off offset:128
	s_waitcnt vmcnt(11)
	v_mfma_f32_16x16x32_bf16 v[66:69], v[100:103], v[132:135], v[66:69]
	global_load_dwordx4 v[100:103], v[84:85], off offset:192
	s_waitcnt vmcnt(11)
; #define LAS __attribute__((address_space(3)))
; __device__ __forceinline__ void small_gemm_q256(LAS unsigned char* lds, const bf16_t* A, const bf16_t* Bt, int unit, const float* SS, float sc, bf16_t* OUT) {
;     ...
; #pragma unroll 2
;     for (int ks = 0; ks < KS; ++ks) {
;         const bf16x8 a = *(const bf16x8*)(ap + 32 * ks);
; #pragma unroll
;         for (int t = 0; t < 16; ++t) { const bf16x8 b = *(const bf16x8*)(bp + (size_t)16 * t * K + 32 * ks); acc[t] = __builtin_amdgcn_mfma_f32_16x16x32_bf16(b, a, acc[t], 0, 0, 0); }
;     }
;     LAS float* red = (LAS float*)lds;
; #pragma unroll
;     for (int t = 0; t < 16; ++t) *(LAS f32x4*)(red + (wave * 16 + li) * 256 + 16 * t + 4 * g4) = acc[t];
;     __syncthreads();
;     float sm = 0.f;
; #pragma unroll
;     for (int q = 0; q < 4; ++q) sm += (sv[q][0] + sv[q][1]) + (sv[q][2] + sv[q][3]);
	v_mfma_f32_16x16x32_bf16 v[62:65], v[104:107], v[132:135], v[62:65]
	global_load_dwordx4 v[104:107], v[86:87], off offset:192
	s_waitcnt vmcnt(11)
	v_mfma_f32_16x16x32_bf16 v[58:61], v[88:91], v[132:135], v[58:61]
	v_lshl_add_u64 v[144:145], v[86:87], 0, s[0:1]
	global_load_dwordx4 v[88:91], v[144:145], off offset:192
	s_waitcnt vmcnt(11)
	v_mfma_f32_16x16x32_bf16 v[54:57], v[116:119], v[132:135], v[54:57]
	v_lshl_add_u64 v[146:147], v[144:145], 0, s[0:1]
	global_load_dwordx4 v[116:119], v[146:147], off offset:192
	s_waitcnt vmcnt(11)
	v_mfma_f32_16x16x32_bf16 v[50:53], v[120:123], v[132:135], v[50:53]
	v_lshl_add_u64 v[144:145], v[146:147], 0, s[0:1]
	global_load_dwordx4 v[120:123], v[144:145], off offset:192
	s_waitcnt vmcnt(11)
	v_mfma_f32_16x16x32_bf16 v[42:45], v[124:127], v[132:135], v[42:45]
	v_lshl_add_u64 v[146:147], v[144:145], 0, s[0:1]
	global_load_dwordx4 v[124:127], v[146:147], off offset:192
	s_waitcnt vmcnt(11)
	v_mfma_f32_16x16x32_bf16 v[38:41], v[128:131], v[132:135], v[38:41]
	v_lshl_add_u64 v[144:145], v[146:147], 0, s[0:1]
	global_load_dwordx4 v[128:131], v[144:145], off offset:192
	s_waitcnt vmcnt(11)
	v_mfma_f32_16x16x32_bf16 v[34:37], v[108:111], v[132:135], v[34:37]
	v_lshl_add_u64 v[146:147], v[144:145], 0, s[0:1]
	global_load_dwordx4 v[108:111], v[146:147], off offset:192
	s_waitcnt vmcnt(11)
	v_mfma_f32_16x16x32_bf16 v[30:33], v[136:139], v[132:135], v[30:33]
	v_lshl_add_u64 v[144:145], v[146:147], 0, s[0:1]
	global_load_dwordx4 v[136:139], v[144:145], off offset:192
	s_waitcnt vmcnt(11)
	v_mfma_f32_16x16x32_bf16 v[26:29], v[140:143], v[132:135], v[26:29]
	v_lshl_add_u64 v[146:147], v[144:145], 0, s[0:1]
	global_load_dwordx4 v[140:143], v[146:147], off offset:192
	s_waitcnt vmcnt(11)
	v_mfma_f32_16x16x32_bf16 v[22:25], v[92:95], v[132:135], v[22:25]
	v_lshl_add_u64 v[144:145], v[146:147], 0, s[0:1]
	global_load_dwordx4 v[92:95], v[144:145], off offset:192
	s_waitcnt vmcnt(11)
	v_mfma_f32_16x16x32_bf16 v[18:21], v[96:99], v[132:135], v[18:21]
	v_lshl_add_u64 v[146:147], v[144:145], 0, s[0:1]
	global_load_dwordx4 v[96:99], v[146:147], off offset:192
	v_lshl_add_u64 v[144:145], v[146:147], 0, s[0:1]
	global_load_dwordx4 v[132:135], v[144:145], off offset:192
	s_waitcnt vmcnt(11)
	v_mfma_f32_16x16x32_bf16 v[46:49], v[104:107], v[100:103], v[46:49]
	v_lshl_add_u64 v[146:147], v[144:145], 0, s[0:1]
	global_load_dwordx4 v[104:107], v[146:147], off offset:192
	s_waitcnt vmcnt(11)
	v_mfma_f32_16x16x32_bf16 v[78:81], v[88:91], v[100:103], v[78:81]
	v_lshl_add_u64 v[144:145], v[146:147], 0, s[0:1]
	global_load_dwordx4 v[88:91], v[144:145], off offset:192
	s_waitcnt vmcnt(11)
	v_mfma_f32_16x16x32_bf16 v[74:77], v[116:119], v[100:103], v[74:77]
	v_lshl_add_u64 v[146:147], v[144:145], 0, s[0:1]
	global_load_dwordx4 v[116:119], v[146:147], off offset:192
	s_waitcnt vmcnt(11)
	v_mfma_f32_16x16x32_bf16 v[70:73], v[120:123], v[100:103], v[70:73]
	v_lshl_add_u64 v[144:145], v[146:147], 0, s[0:1]
	global_load_dwordx4 v[120:123], v[144:145], off offset:192
	s_waitcnt vmcnt(11)
	v_mfma_f32_16x16x32_bf16 v[66:69], v[124:127], v[100:103], v[66:69]
	s_waitcnt vmcnt(10)
	v_mfma_f32_16x16x32_bf16 v[62:65], v[128:131], v[100:103], v[62:65]
	s_waitcnt vmcnt(9)
	v_mfma_f32_16x16x32_bf16 v[58:61], v[108:111], v[100:103], v[58:61]
	s_waitcnt vmcnt(8)
	v_mfma_f32_16x16x32_bf16 v[54:57], v[136:139], v[100:103], v[54:57]
	s_waitcnt vmcnt(7)
	v_mfma_f32_16x16x32_bf16 v[50:53], v[140:143], v[100:103], v[50:53]
	s_waitcnt vmcnt(6)
	v_mfma_f32_16x16x32_bf16 v[42:45], v[92:95], v[100:103], v[42:45]
	s_waitcnt vmcnt(5)
	v_mfma_f32_16x16x32_bf16 v[38:41], v[96:99], v[100:103], v[38:41]
	s_waitcnt vmcnt(4)
	v_mfma_f32_16x16x32_bf16 v[34:37], v[132:135], v[100:103], v[34:37]
	s_waitcnt vmcnt(3)
	v_mfma_f32_16x16x32_bf16 v[30:33], v[104:107], v[100:103], v[30:33]
	s_waitcnt vmcnt(2)
	v_mfma_f32_16x16x32_bf16 v[26:29], v[88:91], v[100:103], v[26:29]
	s_waitcnt vmcnt(1)
	v_mfma_f32_16x16x32_bf16 v[22:25], v[116:119], v[100:103], v[22:25]
	s_waitcnt vmcnt(0)
	v_mfma_f32_16x16x32_bf16 v[18:21], v[120:123], v[100:103], v[18:21]
	s_nop 1
	s_lshl_b32 s0, s14, 8
	v_and_b32_e32 v0, 3, v114
	s_and_b32 s15, s0, 0x300
	s_lshl_b32 s0, s3, 14
	s_add_i32 s0, s0, 0
	v_lshlrev_b32_e32 v0, 4, v0
	v_add3_u32 v0, s0, v115, v0
	ds_write_b128 v0, v[46:49]
	ds_write_b128 v0, v[78:81] offset:64
	ds_write_b128 v0, v[74:77] offset:128
	ds_write_b128 v0, v[70:73] offset:192
	ds_write_b128 v0, v[66:69] offset:256
	ds_write_b128 v0, v[62:65] offset:320
	ds_write_b128 v0, v[58:61] offset:384
	ds_write_b128 v0, v[54:57] offset:448
	ds_write_b128 v0, v[50:53] offset:512
	ds_write_b128 v0, v[42:45] offset:576
	ds_write_b128 v0, v[38:41] offset:640
	ds_write_b128 v0, v[34:37] offset:704
	ds_write_b128 v0, v[30:33] offset:768
	ds_write_b128 v0, v[26:29] offset:832
	ds_write_b128 v0, v[22:25] offset:896
	ds_write_b128 v0, v[18:21] offset:960
	v_mov_b32_e32 v18, v15
	v_mov_b32_e32 v19, v16
	v_mov_b32_e32 v15, v17
	v_mov_b32_e32 v16, v11
	v_mov_b32_e32 v17, v12
	v_mov_b32_e32 v11, v13
	v_pk_add_f32 v[14:15], v[18:19], v[14:15]
	v_pk_add_f32 v[10:11], v[16:17], v[10:11]
	v_add_f32_e32 v0, v14, v15
	v_pk_add_f32 v[10:11], v[10:11], v[10:11] op_sel:[0,1] op_sel_hi:[1,0]
	v_add_f32_e32 v14, 0, v0
	v_add_f32_e32 v6, v6, v7
	v_add_f32_e32 v8, v8, v9
	v_mov_b32_e32 v15, v2
	v_mov_b32_e32 v11, v3
	v_mov_b32_e32 v7, v4
	v_mov_b32_e32 v9, v5
	v_pk_add_f32 v[2:3], v[14:15], v[10:11]
	v_pk_add_f32 v[4:5], v[6:7], v[8:9]
	s_waitcnt lgkmcnt(0)
	v_pk_add_f32 v[2:3], v[2:3], v[4:5]
	s_barrier
; #define LAS __attribute__((address_space(3)))
; __device__ __forceinline__ unsigned cvt_pk_bf16(float lo, float hi) { unsigned r; asm("v_cvt_pk_bf16_f32 %0, %1, %2" : "=v"(r) : "v"(lo), "v"(hi)); return r; }
; __device__ __forceinline__ bf16x8 load8f_bf(const float* p) { const f32x4 a = *(const f32x4*)p, b = *(const f32x4*)(p + 4); return pack8v(a, b); }
; __device__ __forceinline__ int voff_x(int key, int d) { return ((key >> 3) * 8 + (d >> 5)) * 512 + (key & 7) * 64 + (d & 31) * 2; }
; __device__ __forceinline__ void small_gemm_q256(LAS unsigned char* lds, const bf16_t* A, const bf16_t* Bt, int unit, const float* SS, float sc, bf16_t* OUT) {
;     ...
;     const float rs = __builtin_amdgcn_rsqf(sm * (1.0f / 1024.0f) + EPS) * sc;
; #pragma unroll
;     for (int cc = 0; cc < 2; ++cc) {
;         const int c4 = (tid & 31) * 4 + 128 * cc;
;         f32x4 sum = *(LAS f32x4*)(red + row * 256 + c4);
; #pragma unroll
;         for (int w = 1; w < 8; ++w) sum += *(LAS f32x4*)(red + (w * 16 + row) * 256 + c4);
;         u32x2 w; w.x = cvt_pk_bf16(sum[0] * rs, sum[1] * rs); w.y = cvt_pk_bf16(sum[2] * rs, sum[3] * rs);
;         *(u32x2*)(OUT + (size_t)(row0 + row) * D + col0 + c4) = w;
;     }
;     asm volatile("s_waitcnt vmcnt(0)" ::: "memory");
;     __syncthreads();
; __device__ __forceinline__ void xattn_sample_unit(const Params& P, int l, int b, int h, LAS unsigned char* lds, int tid_) {
;     int tid = tid_; asm volatile("" : "+v"(tid));
;     const int lane = tid & 63, wave = __builtin_amdgcn_readfirstlane(tid >> 6), r = lane & 31, hi = lane >> 5;
;     const bf16_t* Q2 = (const bf16_t*)(P.ws + WS_Q2);
;     bf16_t* O2 = (bf16_t*)(P.ws + WS_O2);
;     const float* CK = P.in[7] + ((size_t)(l * 32 + b) * 256 + 32 * wave) * 1024 + h * 256;
;     const float* CV = P.in[8] + ((size_t)(l * 32 + b) * 256 + 32 * wave) * 1024 + h * 256;
;     LAS unsigned char* wl = lds + wave * 16384;
;     LAS float* ml = (LAS float*)(lds + 131072);
;     const int qrow = TP + b * 16 + (r & 15);
; #pragma unroll 4
;     for (int i = 0; i < 16; ++i) { const int idx = lane + 64 * i, vr = idx >> 5, ch = idx & 31;
;         *(LAS bf16x8*)(wl + voff_x(vr, 8 * ch)) = load8f_bf(CV + (size_t)vr * 1024 + 8 * ch); }
;     f32x16 S;
; #pragma unroll
;     for (int e = 0; e < 16; ++e) S[e] = 0.f;
	v_add_f32_e32 v0, v2, v3
	v_fmamk_f32 v0, v0, 0x3a800000, v209
	v_rsq_f32_e32 v0, v0
	v_lshlrev_b32_e32 v2, 10, v113
	v_lshlrev_b64 v[10:11], 11, v[82:83]
	v_mul_f32_e32 v20, 0x3db8aa3b, v0
	v_lshlrev_b32_e32 v0, 2, v112
	v_and_b32_e32 v0, 0x7c, v0
	v_lshlrev_b32_e32 v3, 2, v0
	v_add3_u32 v21, 0, v2, v3
	ds_read_b128 v[2:5], v21
	ds_read_b128 v[6:9], v21 offset:16384
	v_lshl_add_u64 v[14:15], s[30:31], 0, v[10:11]
	ds_read_b128 v[10:13], v21 offset:32768
	s_lshl_b32 s62, s15, 1
	v_lshl_add_u64 v[14:15], v[14:15], 0, s[62:63]
	s_waitcnt lgkmcnt(1)
	v_pk_add_f32 v[6:7], v[2:3], v[6:7]
	v_pk_add_f32 v[8:9], v[4:5], v[8:9]
	ds_read_b128 v[2:5], v21 offset:49152
	s_waitcnt lgkmcnt(1)
	v_pk_add_f32 v[10:11], v[6:7], v[10:11]
	v_add_u32_e32 v6, 0x10000, v21
	v_pk_add_f32 v[12:13], v[8:9], v[12:13]
	ds_read_b128 v[6:9], v6
	s_waitcnt lgkmcnt(1)
	v_pk_add_f32 v[10:11], v[10:11], v[2:3]
	v_add_u32_e32 v2, 0x14000, v21
	v_pk_add_f32 v[12:13], v[12:13], v[4:5]
	ds_read_b128 v[2:5], v2
	s_waitcnt lgkmcnt(1)
	v_pk_add_f32 v[18:19], v[10:11], v[6:7]
	v_add_u32_e32 v6, 0x18000, v21
	v_pk_add_f32 v[16:17], v[12:13], v[8:9]
	ds_read_b128 v[6:9], v6
	v_add_u32_e32 v10, 0x1c000, v21
	ds_read_b128 v[10:13], v10
	s_waitcnt lgkmcnt(2)
	v_pk_add_f32 v[2:3], v[18:19], v[2:3]
	v_pk_add_f32 v[4:5], v[16:17], v[4:5]
	s_waitcnt lgkmcnt(1)
	v_pk_add_f32 v[2:3], v[2:3], v[6:7]
	v_pk_add_f32 v[4:5], v[4:5], v[8:9]
	s_waitcnt lgkmcnt(0)
	v_pk_add_f32 v[2:3], v[2:3], v[10:11]
	v_pk_add_f32 v[4:5], v[4:5], v[12:13]
	v_mul_f32_e32 v2, v20, v2
	v_mul_f32_e32 v3, v20, v3
	v_lshlrev_b32_e32 v0, 1, v0
	v_cvt_pk_bf16_f32 v2, v2, v3
	v_mul_f32_e32 v3, v20, v4
	v_lshl_add_u64 v[14:15], v[14:15], 0, v[0:1]
	v_mul_f32_e32 v4, v20, v5
	v_cvt_pk_bf16_f32 v3, v3, v4
	flat_store_dwordx2 v[14:15], v[2:3]
	ds_read_b128 v[2:5], v21 offset:512
	ds_read_b128 v[6:9], v21 offset:16896
	ds_read_b128 v[10:13], v21 offset:33280
	v_add_u32_e32 v0, 0x10200, v21
	v_mov_b32_e32 v137, v208
	s_ashr_i32 s17, s14, 2
	s_waitcnt lgkmcnt(0)
	v_pk_add_f32 v[8:9], v[4:5], v[8:9]
	v_pk_add_f32 v[6:7], v[2:3], v[6:7]
	ds_read_b128 v[2:5], v21 offset:49664
	v_pk_add_f32 v[12:13], v[8:9], v[12:13]
	v_pk_add_f32 v[10:11], v[6:7], v[10:11]
	ds_read_b128 v[6:9], v0
	v_add_u32_e32 v0, 0x14200, v21
	s_waitcnt lgkmcnt(0)
	v_pk_add_f32 v[12:13], v[12:13], v[4:5]
	v_pk_add_f32 v[10:11], v[10:11], v[2:3]
	ds_read_b128 v[2:5], v0
	v_add_u32_e32 v0, 0x18200, v21
	v_pk_add_f32 v[16:17], v[12:13], v[8:9]
	v_pk_add_f32 v[18:19], v[10:11], v[6:7]
	ds_read_b128 v[6:9], v0
	v_add_u32_e32 v0, 0x1c200, v21
	ds_read_b128 v[10:13], v0
	s_waitcnt lgkmcnt(0)
	v_pk_add_f32 v[4:5], v[16:17], v[4:5]
	v_pk_add_f32 v[2:3], v[18:19], v[2:3]
	v_pk_add_f32 v[4:5], v[4:5], v[8:9]
	v_pk_add_f32 v[2:3], v[2:3], v[6:7]
	v_pk_add_f32 v[4:5], v[4:5], v[12:13]
	v_pk_add_f32 v[2:3], v[2:3], v[10:11]
	s_and_b32 s16, s2, 3
	v_mul_f32_e32 v0, v20, v2
	v_mul_f32_e32 v2, v20, v3
	v_mul_f32_e32 v3, v20, v5
	v_cvt_pk_bf16_f32 v2, v0, v2
	v_mul_f32_e32 v0, v20, v4
	v_cvt_pk_bf16_f32 v3, v0, v3
	flat_store_dwordx2 v[14:15], v[2:3] offset:256
	s_waitcnt vmcnt(0)
	s_waitcnt lgkmcnt(0)
	s_barrier
	s_add_i32 s2, s17, s7
	v_readfirstlane_b32 s0, v137
	s_ashr_i32 s4, s0, 6
	s_lshl_b32 s0, s4, 5
	s_ashr_i32 s3, s2, 31
	s_ashr_i32 s1, s0, 31
	s_lshl_b32 s5, s16, 10
	s_lshl_b32 s4, s4, 14
	s_lshl_b64 s[2:3], s[2:3], 20
	s_lshl_b64 s[24:25], s[0:1], 12
	v_lshlrev_b32_e32 v5, 7, v137
	v_lshlrev_b32_e32 v19, 4, v137
	v_bfe_u32 v18, v137, 5, 1
	s_add_u32 s1, s24, s2
	v_and_b32_e32 v136, 31, v137
	v_and_b32_e32 v5, 0xe00, v5
	v_and_b32_e32 v0, 48, v19
	s_addc_u32 s6, s25, s3
	v_lshl_or_b32 v2, v18, 12, s1
	v_lshlrev_b32_e32 v3, 5, v136
	v_readlane_b32 s36, v253, 7
	v_lshlrev_b32_e32 v4, 6, v18
	v_or_b32_e32 v5, s4, v5
	v_or3_b32 v2, v2, s5, v3
	v_mov_b32_e32 v3, s6
	v_readlane_b32 s37, v253, 8
	v_or3_b32 v0, v5, v4, v0
	v_and_b32_e32 v139, 63, v137
	v_lshl_add_u64 v[2:3], s[36:37], 0, v[2:3]
	v_add_u32_e32 v0, 0, v0
	s_mov_b64 s[26:27], 0
	v_readlane_b32 s38, v253, 9
	v_readlane_b32 s39, v253, 10
	v_readlane_b32 s40, v253, 11
	v_readlane_b32 s41, v253, 12
	v_readlane_b32 s42, v253, 13
	v_readlane_b32 s43, v253, 14
	v_readlane_b32 s44, v253, 15
	v_readlane_b32 s45, v253, 16
	v_readlane_b32 s46, v253, 17
	v_readlane_b32 s47, v253, 18
	v_readlane_b32 s48, v253, 19
	v_readlane_b32 s49, v253, 20
	v_readlane_b32 s50, v253, 21
	v_readlane_b32 s51, v253, 22
	v_mov_b32_e32 v128, v2
	v_mov_b32_e32 v129, v3
	v_mov_b32_e32 v138, v0
	s_lshl_b32 s1, s17, 4
	s_lshl_b32 s6, s16, 9
	v_and_b32_e32 v140, 15, v137
	s_addk_i32 s1, 0x4000
	v_or_b32_e32 v2, s1, v140
	s_add_u32 s1, s24, s2
	v_ashrrev_i32_e32 v3, 31, v2
	s_addc_u32 s3, s25, s3
	v_lshlrev_b64 v[134:135], 11, v[2:3]
	v_lshlrev_b32_e32 v0, 4, v18
	v_readlane_b32 s16, v254, 43
	s_add_u32 s2, s5, s1
	v_or3_b32 v2, v134, s6, v0
	v_mov_b32_e32 v3, v135
	v_readlane_b32 s17, v254, 44
	v_lshlrev_b32_e32 v0, 12, v136
	s_addc_u32 s3, 0, s3
	v_lshl_add_u64 v[20:21], s[16:17], 0, v[2:3]
	v_lshl_add_u64 v[2:3], s[2:3], 0, v[0:1]
	v_lshlrev_b32_e32 v0, 5, v18
	v_readlane_b32 s36, v253, 55
	v_lshl_add_u64 v[2:3], v[2:3], 0, v[0:1]
	v_readlane_b32 s50, v254, 5
	v_readlane_b32 s51, v254, 6
	s_mov_b64 s[2:3], 0
	v_readlane_b32 s37, v253, 56
	v_lshl_add_u64 v[22:23], s[50:51], 0, v[2:3]
	v_mov_b32_e32 v2, 0
	v_mov_b32_e32 v3, v2
	v_mov_b32_e32 v4, v2
	v_mov_b32_e32 v5, v2
	v_mov_b32_e32 v6, v2
	v_mov_b32_e32 v7, v2
	v_mov_b32_e32 v8, v2
	v_mov_b32_e32 v9, v2
	v_mov_b32_e32 v10, v2
	v_mov_b32_e32 v11, v2
	v_mov_b32_e32 v12, v2
	v_mov_b32_e32 v13, v2
	v_mov_b32_e32 v14, v2
	v_mov_b32_e32 v15, v2
	v_mov_b32_e32 v16, v2
	v_mov_b32_e32 v17, v2
; #define LAS __attribute__((address_space(3)))
; __device__ __forceinline__ bf16x8 load8f_bf(const float* p) { const f32x4 a = *(const f32x4*)p, b = *(const f32x4*)(p + 4); return pack8v(a, b); }
; __device__ __forceinline__ int voff_x(int key, int d) { return ((key >> 3) * 8 + (d >> 5)) * 512 + (key & 7) * 64 + (d & 31) * 2; }
; __device__ __forceinline__ void xattn_sample_unit(const Params& P, int l, int b, int h, LAS unsigned char* lds, int tid_) {
;     ...
; #pragma unroll 4
;     for (int i = 0; i < 16; ++i) { const int idx = lane + 64 * i, vr = idx >> 5, ch = idx & 31;
;         *(LAS bf16x8*)(wl + voff_x(vr, 8 * ch)) = load8f_bf(CV + (size_t)vr * 1024 + 8 * ch); }
;     f32x16 S;
; #pragma unroll
;     for (int e = 0; e < 16; ++e) S[e] = 0.f;
; #pragma unroll 4
;     for (int ks = 0; ks < 16; ++ks) {
;         const bf16x8 qf = *(const bf16x8*)(Q2 + (size_t)qrow * D + h * 256 + 16 * ks + 8 * hi);
;         const bf16x8 kf = load8f_bf(CK + (size_t)r * 1024 + 16 * ks + 8 * hi);
;         S = __builtin_amdgcn_mfma_f32_32x32x16_bf16(kf, qf, S, 0, 0, 0);
;     }
	v_readlane_b32 s38, v253, 57
	v_readlane_b32 s39, v253, 58
	v_readlane_b32 s40, v253, 59
	v_readlane_b32 s41, v253, 60
	v_readlane_b32 s42, v253, 61
	v_readlane_b32 s43, v253, 62
	v_readlane_b32 s44, v253, 63
	v_readlane_b32 s45, v254, 0
	v_readlane_b32 s46, v254, 1
	v_readlane_b32 s47, v254, 2
	v_readlane_b32 s48, v254, 3
	v_readlane_b32 s49, v254, 4
	s_mov_b64 s[26:27], 0x8000
	v_lshl_add_u64 v[130:131], v[128:129], 0, s[26:27]
	v_lshl_add_u64 v[132:133], v[130:131], 0, s[26:27]
	v_lshl_add_u64 v[142:143], v[132:133], 0, s[26:27]
	global_load_dwordx4 v[24:27], v[128:129], off
	global_load_dwordx4 v[28:31], v[128:129], off offset:16
	v_lshl_add_u64 v[144:145], v[128:129], 0, s[72:73]
	global_load_dwordx4 v[32:35], v[144:145], off
	global_load_dwordx4 v[36:39], v[144:145], off offset:16
	v_lshl_add_u64 v[144:145], v[128:129], 0, s[74:75]
	global_load_dwordx4 v[40:43], v[144:145], off
	global_load_dwordx4 v[44:47], v[144:145], off offset:16
	v_lshl_add_u64 v[144:145], v[128:129], 0, s[76:77]
	global_load_dwordx4 v[48:51], v[144:145], off
	global_load_dwordx4 v[52:55], v[144:145], off offset:16
	global_load_dwordx4 v[56:59], v[130:131], off
	global_load_dwordx4 v[60:63], v[130:131], off offset:16
	v_lshl_add_u64 v[144:145], v[130:131], 0, s[72:73]
	global_load_dwordx4 v[64:67], v[144:145], off
	global_load_dwordx4 v[68:71], v[144:145], off offset:16
	v_lshl_add_u64 v[144:145], v[130:131], 0, s[74:75]
	global_load_dwordx4 v[72:75], v[144:145], off
	global_load_dwordx4 v[76:79], v[144:145], off offset:16
	v_lshl_add_u64 v[144:145], v[130:131], 0, s[76:77]
	global_load_dwordx4 v[80:83], v[144:145], off
	global_load_dwordx4 v[84:87], v[144:145], off offset:16
	global_load_dwordx4 v[88:91], v[132:133], off
	global_load_dwordx4 v[92:95], v[132:133], off offset:16
	v_lshl_add_u64 v[144:145], v[132:133], 0, s[72:73]
	global_load_dwordx4 v[96:99], v[144:145], off
	global_load_dwordx4 v[100:103], v[144:145], off offset:16
	v_lshl_add_u64 v[144:145], v[132:133], 0, s[74:75]
	global_load_dwordx4 v[104:107], v[144:145], off
	global_load_dwordx4 v[108:111], v[144:145], off offset:16
	v_lshl_add_u64 v[144:145], v[132:133], 0, s[76:77]
	global_load_dwordx4 v[112:115], v[144:145], off
	global_load_dwordx4 v[116:119], v[144:145], off offset:16
	global_load_dwordx4 v[120:123], v[142:143], off
	global_load_dwordx4 v[124:127], v[142:143], off offset:16
	s_waitcnt vmcnt(24)
	v_cvt_pk_bf16_f32 v24, v24, v25
	v_cvt_pk_bf16_f32 v25, v26, v27
	v_cvt_pk_bf16_f32 v26, v28, v29
	v_cvt_pk_bf16_f32 v27, v30, v31
	ds_write_b128 v138, v[24:27]
	v_lshl_add_u64 v[144:145], v[142:143], 0, s[72:73]
	global_load_dwordx4 v[24:27], v[144:145], off
	global_load_dwordx4 v[28:31], v[144:145], off offset:16
	s_waitcnt vmcnt(24)
	v_cvt_pk_bf16_f32 v32, v32, v33
	v_cvt_pk_bf16_f32 v33, v34, v35
	v_cvt_pk_bf16_f32 v34, v36, v37
	v_cvt_pk_bf16_f32 v35, v38, v39
	ds_write_b128 v138, v[32:35] offset:128
	v_lshl_add_u64 v[144:145], v[142:143], 0, s[74:75]
	global_load_dwordx4 v[32:35], v[144:145], off
	global_load_dwordx4 v[36:39], v[144:145], off offset:16
	s_waitcnt vmcnt(24)
	v_cvt_pk_bf16_f32 v40, v40, v41
	v_cvt_pk_bf16_f32 v41, v42, v43
	v_cvt_pk_bf16_f32 v42, v44, v45
	v_cvt_pk_bf16_f32 v43, v46, v47
	ds_write_b128 v138, v[40:43] offset:256
	v_lshl_add_u64 v[144:145], v[142:143], 0, s[76:77]
	global_load_dwordx4 v[40:43], v[144:145], off
	global_load_dwordx4 v[44:47], v[144:145], off offset:16
	s_waitcnt vmcnt(24)
	v_cvt_pk_bf16_f32 v48, v48, v49
	v_cvt_pk_bf16_f32 v49, v50, v51
	v_cvt_pk_bf16_f32 v50, v52, v53
	v_cvt_pk_bf16_f32 v51, v54, v55
	ds_write_b128 v138, v[48:51] offset:384
	global_load_dwordx4 v[48:51], v[20:21], off offset:-64
	global_load_dwordx4 v[52:55], v[22:23], off
	s_waitcnt vmcnt(24)
	v_cvt_pk_bf16_f32 v56, v56, v57
	v_cvt_pk_bf16_f32 v57, v58, v59
	v_cvt_pk_bf16_f32 v58, v60, v61
	v_cvt_pk_bf16_f32 v59, v62, v63
	ds_write_b128 v138, v[56:59] offset:4096
	global_load_dwordx4 v[56:59], v[22:23], off offset:16
	global_load_dwordx4 v[60:63], v[20:21], off offset:-32
	s_waitcnt vmcnt(24)
	v_cvt_pk_bf16_f32 v64, v64, v65
	v_cvt_pk_bf16_f32 v65, v66, v67
	v_cvt_pk_bf16_f32 v66, v68, v69
	v_cvt_pk_bf16_f32 v67, v70, v71
	ds_write_b128 v138, v[64:67] offset:4224
	global_load_dwordx4 v[64:67], v[22:23], off offset:64
	global_load_dwordx4 v[68:71], v[22:23], off offset:80
	s_waitcnt vmcnt(24)
	v_cvt_pk_bf16_f32 v72, v72, v73
	v_cvt_pk_bf16_f32 v73, v74, v75
	v_cvt_pk_bf16_f32 v74, v76, v77
	v_cvt_pk_bf16_f32 v75, v78, v79
	ds_write_b128 v138, v[72:75] offset:4352
	global_load_dwordx4 v[72:75], v[20:21], off
	global_load_dwordx4 v[76:79], v[22:23], off offset:128
	s_waitcnt vmcnt(24)
	v_cvt_pk_bf16_f32 v80, v80, v81
	v_cvt_pk_bf16_f32 v81, v82, v83
	v_cvt_pk_bf16_f32 v82, v84, v85
	v_cvt_pk_bf16_f32 v83, v86, v87
	ds_write_b128 v138, v[80:83] offset:4480
	global_load_dwordx4 v[80:83], v[22:23], off offset:144
	global_load_dwordx4 v[84:87], v[20:21], off offset:32
	s_waitcnt vmcnt(24)
	v_cvt_pk_bf16_f32 v88, v88, v89
	v_cvt_pk_bf16_f32 v89, v90, v91
	v_cvt_pk_bf16_f32 v90, v92, v93
	v_cvt_pk_bf16_f32 v91, v94, v95
	ds_write_b128 v138, v[88:91] offset:8192
	global_load_dwordx4 v[88:91], v[22:23], off offset:192
	global_load_dwordx4 v[92:95], v[22:23], off offset:208
	s_waitcnt vmcnt(24)
	v_cvt_pk_bf16_f32 v96, v96, v97
	v_cvt_pk_bf16_f32 v97, v98, v99
	v_cvt_pk_bf16_f32 v98, v100, v101
	v_cvt_pk_bf16_f32 v99, v102, v103
	ds_write_b128 v138, v[96:99] offset:8320
	global_load_dwordx4 v[96:99], v[20:21], off offset:64
	global_load_dwordx4 v[100:103], v[22:23], off offset:256
	s_waitcnt vmcnt(24)
; #define LAS __attribute__((address_space(3)))
; __device__ __forceinline__ bf16x8 load8f_bf(const float* p) { const f32x4 a = *(const f32x4*)p, b = *(const f32x4*)(p + 4); return pack8v(a, b); }
; __device__ __forceinline__ int voff_x(int key, int d) { return ((key >> 3) * 8 + (d >> 5)) * 512 + (key & 7) * 64 + (d & 31) * 2; }
; __device__ __forceinline__ void xattn_sample_unit(const Params& P, int l, int b, int h, LAS unsigned char* lds, int tid_) {
;     ...
;     for (int i = 0; i < 16; ++i) { const int idx = lane + 64 * i, vr = idx >> 5, ch = idx & 31;
;         *(LAS bf16x8*)(wl + voff_x(vr, 8 * ch)) = load8f_bf(CV + (size_t)vr * 1024 + 8 * ch); }
;     f32x16 S;
; #pragma unroll
;     for (int e = 0; e < 16; ++e) S[e] = 0.f;
; #pragma unroll 4
;     for (int ks = 0; ks < 16; ++ks) {
;         const bf16x8 qf = *(const bf16x8*)(Q2 + (size_t)qrow * D + h * 256 + 16 * ks + 8 * hi);
;         const bf16x8 kf = load8f_bf(CK + (size_t)r * 1024 + 16 * ks + 8 * hi);
;         S = __builtin_amdgcn_mfma_f32_32x32x16_bf16(kf, qf, S, 0, 0, 0);
;     }
	v_cvt_pk_bf16_f32 v104, v104, v105
	v_cvt_pk_bf16_f32 v105, v106, v107
	v_cvt_pk_bf16_f32 v106, v108, v109
	v_cvt_pk_bf16_f32 v107, v110, v111
	ds_write_b128 v138, v[104:107] offset:8448
	global_load_dwordx4 v[104:107], v[22:23], off offset:272
	global_load_dwordx4 v[108:111], v[20:21], off offset:96
	s_waitcnt vmcnt(24)
	v_cvt_pk_bf16_f32 v112, v112, v113
	v_cvt_pk_bf16_f32 v113, v114, v115
	v_cvt_pk_bf16_f32 v114, v116, v117
	v_cvt_pk_bf16_f32 v115, v118, v119
	ds_write_b128 v138, v[112:115] offset:8576
	global_load_dwordx4 v[112:115], v[22:23], off offset:320
	global_load_dwordx4 v[116:119], v[22:23], off offset:336
	s_waitcnt vmcnt(24)
	v_cvt_pk_bf16_f32 v120, v120, v121
	v_cvt_pk_bf16_f32 v121, v122, v123
	v_cvt_pk_bf16_f32 v122, v124, v125
	v_cvt_pk_bf16_f32 v123, v126, v127
	ds_write_b128 v138, v[120:123] offset:12288
	global_load_dwordx4 v[120:123], v[20:21], off offset:128
	global_load_dwordx4 v[124:127], v[22:23], off offset:384
	s_waitcnt vmcnt(24)
	v_cvt_pk_bf16_f32 v24, v24, v25
	v_cvt_pk_bf16_f32 v25, v26, v27
	v_cvt_pk_bf16_f32 v26, v28, v29
	v_cvt_pk_bf16_f32 v27, v30, v31
	ds_write_b128 v138, v[24:27] offset:12416
	global_load_dwordx4 v[24:27], v[22:23], off offset:400
	global_load_dwordx4 v[28:31], v[20:21], off offset:160
	s_waitcnt vmcnt(24)
	v_cvt_pk_bf16_f32 v32, v32, v33
	v_cvt_pk_bf16_f32 v33, v34, v35
	v_cvt_pk_bf16_f32 v34, v36, v37
	v_cvt_pk_bf16_f32 v35, v38, v39
	ds_write_b128 v138, v[32:35] offset:12544
	global_load_dwordx4 v[32:35], v[22:23], off offset:448
	global_load_dwordx4 v[36:39], v[22:23], off offset:464
	s_waitcnt vmcnt(24)
	v_cvt_pk_bf16_f32 v40, v40, v41
	v_cvt_pk_bf16_f32 v41, v42, v43
	v_cvt_pk_bf16_f32 v42, v44, v45
	v_cvt_pk_bf16_f32 v43, v46, v47
	ds_write_b128 v138, v[40:43] offset:12672
	global_load_dwordx4 v[40:43], v[20:21], off offset:192
	global_load_dwordx4 v[44:47], v[22:23], off offset:512
	s_waitcnt vmcnt(23)
	v_cvt_pk_bf16_f32 v52, v52, v53
	v_cvt_pk_bf16_f32 v53, v54, v55
	v_cvt_pk_bf16_f32 v54, v56, v57
	v_cvt_pk_bf16_f32 v55, v58, v59
	s_nop 1
	v_mfma_f32_32x32x16_bf16 v[2:17], v[52:55], v[48:51], v[2:17]
	global_load_dwordx4 v[48:51], v[22:23], off offset:528
	global_load_dwordx4 v[52:55], v[20:21], off offset:224
	global_load_dwordx4 v[56:59], v[22:23], off offset:576
	s_waitcnt vmcnt(23)
	v_cvt_pk_bf16_f32 v64, v64, v65
	v_cvt_pk_bf16_f32 v65, v66, v67
	v_cvt_pk_bf16_f32 v66, v68, v69
	v_cvt_pk_bf16_f32 v67, v70, v71
	s_nop 1
	v_mfma_f32_32x32x16_bf16 v[2:17], v[64:67], v[60:63], v[2:17]
	global_load_dwordx4 v[60:63], v[22:23], off offset:592
	global_load_dwordx4 v[64:67], v[20:21], off offset:256
	global_load_dwordx4 v[68:71], v[22:23], off offset:640
	s_waitcnt vmcnt(23)
	v_cvt_pk_bf16_f32 v76, v76, v77
	v_cvt_pk_bf16_f32 v77, v78, v79
	v_cvt_pk_bf16_f32 v78, v80, v81
	v_cvt_pk_bf16_f32 v79, v82, v83
	s_nop 1
	v_mfma_f32_32x32x16_bf16 v[2:17], v[76:79], v[72:75], v[2:17]
	global_load_dwordx4 v[72:75], v[22:23], off offset:656
	global_load_dwordx4 v[76:79], v[20:21], off offset:288
	global_load_dwordx4 v[80:83], v[22:23], off offset:704
	s_waitcnt vmcnt(23)
	v_cvt_pk_bf16_f32 v88, v88, v89
	v_cvt_pk_bf16_f32 v89, v90, v91
	v_cvt_pk_bf16_f32 v90, v92, v93
	v_cvt_pk_bf16_f32 v91, v94, v95
	s_nop 1
	v_mfma_f32_32x32x16_bf16 v[2:17], v[88:91], v[84:87], v[2:17]
	global_load_dwordx4 v[84:87], v[22:23], off offset:720
	global_load_dwordx4 v[88:91], v[20:21], off offset:320
	global_load_dwordx4 v[92:95], v[22:23], off offset:768
	s_waitcnt vmcnt(23)
	v_cvt_pk_bf16_f32 v100, v100, v101
	v_cvt_pk_bf16_f32 v101, v102, v103
	v_cvt_pk_bf16_f32 v102, v104, v105
	v_cvt_pk_bf16_f32 v103, v106, v107
	s_nop 1
	v_mfma_f32_32x32x16_bf16 v[2:17], v[100:103], v[96:99], v[2:17]
	global_load_dwordx4 v[96:99], v[22:23], off offset:784
	global_load_dwordx4 v[100:103], v[20:21], off offset:352
	global_load_dwordx4 v[104:107], v[22:23], off offset:832
	s_waitcnt vmcnt(23)
	v_cvt_pk_bf16_f32 v112, v112, v113
	v_cvt_pk_bf16_f32 v113, v114, v115
	v_cvt_pk_bf16_f32 v114, v116, v117
	v_cvt_pk_bf16_f32 v115, v118, v119
	s_nop 1
	v_mfma_f32_32x32x16_bf16 v[2:17], v[112:115], v[108:111], v[2:17]
	global_load_dwordx4 v[108:111], v[22:23], off offset:848
	global_load_dwordx4 v[112:115], v[20:21], off offset:384
	global_load_dwordx4 v[116:119], v[22:23], off offset:896
	s_waitcnt vmcnt(23)
	v_cvt_pk_bf16_f32 v124, v124, v125
	v_cvt_pk_bf16_f32 v125, v126, v127
	v_cvt_pk_bf16_f32 v126, v24, v25
	v_cvt_pk_bf16_f32 v127, v26, v27
	s_nop 1
	v_mfma_f32_32x32x16_bf16 v[2:17], v[124:127], v[120:123], v[2:17]
	global_load_dwordx4 v[120:123], v[22:23], off offset:912
	global_load_dwordx4 v[124:127], v[20:21], off offset:416
	global_load_dwordx4 v[24:27], v[22:23], off offset:960
	s_waitcnt vmcnt(23)
	v_cvt_pk_bf16_f32 v32, v32, v33
	v_cvt_pk_bf16_f32 v33, v34, v35
	v_cvt_pk_bf16_f32 v34, v36, v37
	v_cvt_pk_bf16_f32 v35, v38, v39
	s_nop 1
	v_mfma_f32_32x32x16_bf16 v[2:17], v[32:35], v[28:31], v[2:17]
	global_load_dwordx4 v[28:31], v[22:23], off offset:976
	s_waitcnt vmcnt(21)
	v_cvt_pk_bf16_f32 v44, v44, v45
	v_cvt_pk_bf16_f32 v45, v46, v47
	v_cvt_pk_bf16_f32 v46, v48, v49
	v_cvt_pk_bf16_f32 v47, v50, v51
	s_nop 1
	v_mfma_f32_32x32x16_bf16 v[2:17], v[44:47], v[40:43], v[2:17]
	s_waitcnt vmcnt(18)
	v_cvt_pk_bf16_f32 v56, v56, v57
	v_cvt_pk_bf16_f32 v57, v58, v59
	v_cvt_pk_bf16_f32 v58, v60, v61
	v_cvt_pk_bf16_f32 v59, v62, v63
	s_nop 1
	v_mfma_f32_32x32x16_bf16 v[2:17], v[56:59], v[52:55], v[2:17]
	s_waitcnt vmcnt(15)
	v_cvt_pk_bf16_f32 v68, v68, v69
	v_cvt_pk_bf16_f32 v69, v70, v71
	v_cvt_pk_bf16_f32 v70, v72, v73
	v_cvt_pk_bf16_f32 v71, v74, v75
	s_nop 1
	v_mfma_f32_32x32x16_bf16 v[2:17], v[68:71], v[64:67], v[2:17]
	s_waitcnt vmcnt(12)
; __device__ __forceinline__ unsigned cvt_pk_bf16(float lo, float hi) { unsigned r; asm("v_cvt_pk_bf16_f32 %0, %1, %2" : "=v"(r) : "v"(lo), "v"(hi)); return r; }
; __device__ __forceinline__ bf16x8 load8f_bf(const float* p) { const f32x4 a = *(const f32x4*)p, b = *(const f32x4*)(p + 4); return pack8v(a, b); }
; __device__ __forceinline__ int voff_x(int key, int d) { return ((key >> 3) * 8 + (d >> 5)) * 512 + (key & 7) * 64 + (d & 31) * 2; }
; __device__ __forceinline__ void xattn_sample_unit(const Params& P, int l, int b, int h, LAS unsigned char* lds, int tid_) {
;     ...
; #pragma unroll 4
;     for (int ks = 0; ks < 16; ++ks) {
;         const bf16x8 qf = *(const bf16x8*)(Q2 + (size_t)qrow * D + h * 256 + 16 * ks + 8 * hi);
;         const bf16x8 kf = load8f_bf(CK + (size_t)r * 1024 + 16 * ks + 8 * hi);
;         S = __builtin_amdgcn_mfma_f32_32x32x16_bf16(kf, qf, S, 0, 0, 0);
;     }
;     float mx = S[0];
; #pragma unroll
;     for (int e = 1; e < 16; ++e) mx = fmaxf(mx, S[e]);
;     mx = fmaxf(mx, __shfl_xor(mx, 32));
;     float ls = 0.f;
; #pragma unroll
;     for (int e = 0; e < 16; ++e) { S[e] = __builtin_amdgcn_exp2f(S[e] - mx); ls += S[e]; }
;     ls += __shfl_xor(ls, 32);
;     bf16x8 pf[2];
; #pragma unroll
;     for (int s2 = 0; s2 < 2; ++s2) { u32x4 w; w.x = cvt_pk_bf16(S[8 * s2 + 0], S[8 * s2 + 1]); w.y = cvt_pk_bf16(S[8 * s2 + 2], S[8 * s2 + 3]); w.z = cvt_pk_bf16(S[8 * s2 + 4], S[8 * s2 + 5]); w.w = cvt_pk_bf16(S[8 * s2 + 6], S[8 * s2 + 7]);
;         pf[s2] = __builtin_bit_cast(bf16x8, w); }
;     f32x16 O[8];
;     const int trow = 4 * hi + ((lane & 15) >> 2), tcol = 16 * ((lane >> 4) & 1) + 4 * (lane & 3);
; #pragma unroll
;     for (int db = 0; db < 8; ++db) {
; #pragma unroll
;         for (int e = 0; e < 16; ++e) O[db][e] = 0.f;
; #pragma unroll
;         for (int s2 = 0; s2 < 2; ++s2) {
;             const s16x4 a0 = tr_read(wl + voff_x(16 * s2 + trow, 32 * db + tcol));
;             const s16x4 a1 = tr_read(wl + voff_x(16 * s2 + 8 + trow, 32 * db + tcol));
;             const bf16x8 vf = (bf16x8){a0[0], a0[1], a0[2], a0[3], a1[0], a1[1], a1[2], a1[3]};
;             O[db] = __builtin_amdgcn_mfma_f32_32x32x16_bf16(vf, pf[s2], O[db], 0, 0, 0);
;         }
;     }
;     if (lane < 16) { ml[(wave * 16 + lane) * 2] = mx; ml[(wave * 16 + lane) * 2 + 1] = ls; }
	v_cvt_pk_bf16_f32 v80, v80, v81
	v_cvt_pk_bf16_f32 v81, v82, v83
	v_cvt_pk_bf16_f32 v82, v84, v85
	v_cvt_pk_bf16_f32 v83, v86, v87
	s_nop 1
	v_mfma_f32_32x32x16_bf16 v[2:17], v[80:83], v[76:79], v[2:17]
	s_waitcnt vmcnt(9)
	v_cvt_pk_bf16_f32 v92, v92, v93
	v_cvt_pk_bf16_f32 v93, v94, v95
	v_cvt_pk_bf16_f32 v94, v96, v97
	v_cvt_pk_bf16_f32 v95, v98, v99
	s_nop 1
	v_mfma_f32_32x32x16_bf16 v[2:17], v[92:95], v[88:91], v[2:17]
	s_waitcnt vmcnt(6)
	v_cvt_pk_bf16_f32 v104, v104, v105
	v_cvt_pk_bf16_f32 v105, v106, v107
	v_cvt_pk_bf16_f32 v106, v108, v109
	v_cvt_pk_bf16_f32 v107, v110, v111
	s_nop 1
	v_mfma_f32_32x32x16_bf16 v[2:17], v[104:107], v[100:103], v[2:17]
	s_waitcnt vmcnt(3)
	v_cvt_pk_bf16_f32 v116, v116, v117
	v_cvt_pk_bf16_f32 v117, v118, v119
	v_cvt_pk_bf16_f32 v118, v120, v121
	v_cvt_pk_bf16_f32 v119, v122, v123
	s_nop 1
	v_mfma_f32_32x32x16_bf16 v[2:17], v[116:119], v[112:115], v[2:17]
	s_waitcnt vmcnt(0)
	v_cvt_pk_bf16_f32 v24, v24, v25
	v_cvt_pk_bf16_f32 v25, v26, v27
	v_cvt_pk_bf16_f32 v26, v28, v29
	v_cvt_pk_bf16_f32 v27, v30, v31
	s_nop 1
	v_mfma_f32_32x32x16_bf16 v[2:17], v[24:27], v[124:127], v[2:17]
	s_nop 1
	s_nop 10
	v_max_f32_e32 v0, v3, v3
	v_max_f32_e32 v20, v2, v2
	v_max_f32_e32 v0, v20, v0
	v_max3_f32 v0, v0, v4, v5
	v_max3_f32 v0, v0, v6, v7
	v_max3_f32 v0, v0, v8, v9
	v_and_b32_e32 v21, 64, v210
	v_max3_f32 v0, v0, v10, v11
	v_xor_b32_e32 v20, 32, v210
	v_add_u32_e32 v21, 64, v21
	v_max3_f32 v0, v0, v12, v13
	v_cmp_lt_i32_e32 vcc, v20, v21
	v_max3_f32 v0, v0, v14, v15
	v_max3_f32 v0, v0, v16, v17
	v_cndmask_b32_e32 v20, v210, v20, vcc
	v_lshlrev_b32_e32 v20, 2, v20
	ds_bpermute_b32 v21, v20, v0
	s_add_i32 s4, s4, 0
	v_lshlrev_b32_e32 v142, 8, v18
	v_cmp_gt_u32_e32 vcc, 16, v139
	s_waitcnt lgkmcnt(0)
	v_max_f32_e32 v21, v21, v21
	v_max_f32_e32 v138, v0, v21
	v_sub_f32_e32 v0, v2, v138
	v_exp_f32_e32 v2, v0
	v_sub_f32_e32 v3, v3, v138
	v_exp_f32_e32 v3, v3
	v_sub_f32_e32 v4, v4, v138
	v_exp_f32_e32 v4, v4
	v_sub_f32_e32 v5, v5, v138
	v_exp_f32_e32 v5, v5
	v_sub_f32_e32 v6, v6, v138
	v_add_f32_e32 v0, 0, v2
	v_exp_f32_e32 v6, v6
	v_sub_f32_e32 v7, v7, v138
	v_add_f32_e32 v0, v3, v0
	v_exp_f32_e32 v7, v7
	v_sub_f32_e32 v8, v8, v138
	v_add_f32_e32 v0, v4, v0
	v_exp_f32_e32 v8, v8
	v_sub_f32_e32 v9, v9, v138
	v_add_f32_e32 v0, v5, v0
	v_exp_f32_e32 v9, v9
	v_sub_f32_e32 v10, v10, v138
	v_add_f32_e32 v0, v6, v0
	v_exp_f32_e32 v10, v10
	v_sub_f32_e32 v11, v11, v138
	v_add_f32_e32 v0, v7, v0
	v_exp_f32_e32 v11, v11
	v_sub_f32_e32 v12, v12, v138
	v_add_f32_e32 v0, v8, v0
	v_exp_f32_e32 v12, v12
	v_sub_f32_e32 v13, v13, v138
	v_cvt_pk_bf16_f32 v114, v2, v3
	v_and_b32_e32 v2, 16, v137
	v_lshlrev_b32_e32 v3, 2, v137
	v_add_f32_e32 v0, v9, v0
	v_exp_f32_e32 v13, v13
	v_sub_f32_e32 v14, v14, v138
	v_and_or_b32 v2, v3, 12, v2
	v_add_f32_e32 v0, v10, v0
	v_exp_f32_e32 v14, v14
	v_sub_f32_e32 v15, v15, v138
	v_cvt_pk_bf16_f32 v115, v4, v5
	v_and_b32_e32 v3, 0xc0, v19
	v_lshlrev_b32_e32 v2, 1, v2
	v_add_u32_e32 v4, s4, v142
	v_add_f32_e32 v0, v11, v0
	v_exp_f32_e32 v15, v15
	v_sub_f32_e32 v16, v16, v138
	v_add3_u32 v143, v4, v3, v2
	v_add_f32_e32 v0, v12, v0
	v_exp_f32_e32 v16, v16
	v_sub_f32_e32 v17, v17, v138
	ds_read_b64_tr_b16 v[2:3], v143
	ds_read_b64_tr_b16 v[4:5], v143 offset:4096
	v_add_f32_e32 v0, v13, v0
	v_exp_f32_e32 v17, v17
	v_add_f32_e32 v0, v14, v0
	v_add_f32_e32 v0, v15, v0
	v_add_f32_e32 v0, v16, v0
	v_add_f32_e32 v0, v17, v0
	v_cvt_pk_bf16_f32 v116, v6, v7
	v_cvt_pk_bf16_f32 v117, v8, v9
	v_cvt_pk_bf16_f32 v130, v10, v11
	v_cvt_pk_bf16_f32 v131, v12, v13
	v_cvt_pk_bf16_f32 v132, v14, v15
	v_cvt_pk_bf16_f32 v133, v16, v17
	ds_bpermute_b32 v141, v20, v0
	s_waitcnt lgkmcnt(1)
	v_mfma_f32_32x32x16_bf16 v[2:17], v[2:5], v[114:117], 0
	ds_read_b64_tr_b16 v[18:19], v143 offset:8192
	ds_read_b64_tr_b16 v[20:21], v143 offset:12288
	s_waitcnt lgkmcnt(0)
	v_mfma_f32_32x32x16_bf16 v[2:17], v[18:21], v[130:133], v[2:17]
	ds_read_b64_tr_b16 v[18:19], v143 offset:512
	ds_read_b64_tr_b16 v[20:21], v143 offset:4608
	ds_read_b64_tr_b16 v[34:35], v143 offset:8704
	ds_read_b64_tr_b16 v[36:37], v143 offset:12800
	s_waitcnt lgkmcnt(2)
	v_mfma_f32_32x32x16_bf16 v[18:33], v[18:21], v[114:117], 0
	s_waitcnt lgkmcnt(0)
	v_mfma_f32_32x32x16_bf16 v[18:33], v[34:37], v[130:133], v[18:33]
	ds_read_b64_tr_b16 v[34:35], v143 offset:1024
	ds_read_b64_tr_b16 v[36:37], v143 offset:5120
	ds_read_b64_tr_b16 v[50:51], v143 offset:9216
	ds_read_b64_tr_b16 v[52:53], v143 offset:13312
	s_waitcnt lgkmcnt(2)
	v_mfma_f32_32x32x16_bf16 v[34:49], v[34:37], v[114:117], 0
	s_waitcnt lgkmcnt(0)
	v_mfma_f32_32x32x16_bf16 v[34:49], v[50:53], v[130:133], v[34:49]
	ds_read_b64_tr_b16 v[50:51], v143 offset:1536
	ds_read_b64_tr_b16 v[52:53], v143 offset:5632
	ds_read_b64_tr_b16 v[66:67], v143 offset:9728
	ds_read_b64_tr_b16 v[68:69], v143 offset:13824
	s_waitcnt lgkmcnt(2)
	v_mfma_f32_32x32x16_bf16 v[50:65], v[50:53], v[114:117], 0
	s_waitcnt lgkmcnt(0)
	v_mfma_f32_32x32x16_bf16 v[50:65], v[66:69], v[130:133], v[50:65]
	ds_read_b64_tr_b16 v[66:67], v143 offset:2048
	ds_read_b64_tr_b16 v[68:69], v143 offset:6144
	ds_read_b64_tr_b16 v[82:83], v143 offset:10240
	ds_read_b64_tr_b16 v[84:85], v143 offset:14336
	s_waitcnt lgkmcnt(2)
	v_mfma_f32_32x32x16_bf16 v[66:81], v[66:69], v[114:117], 0
	s_waitcnt lgkmcnt(0)
	v_mfma_f32_32x32x16_bf16 v[66:81], v[82:85], v[130:133], v[66:81]
	ds_read_b64_tr_b16 v[82:83], v143 offset:2560
	ds_read_b64_tr_b16 v[84:85], v143 offset:6656
	ds_read_b64_tr_b16 v[98:99], v143 offset:10752
	ds_read_b64_tr_b16 v[100:101], v143 offset:14848
	s_waitcnt lgkmcnt(2)
	v_mfma_f32_32x32x16_bf16 v[82:97], v[82:85], v[114:117], 0
	s_waitcnt lgkmcnt(0)
	v_mfma_f32_32x32x16_bf16 v[82:97], v[98:101], v[130:133], v[82:97]
	ds_read_b64_tr_b16 v[98:99], v143 offset:3072
	ds_read_b64_tr_b16 v[100:101], v143 offset:7168
	ds_read_b64_tr_b16 v[118:119], v143 offset:11264
	ds_read_b64_tr_b16 v[120:121], v143 offset:15360
	s_waitcnt lgkmcnt(2)
	v_mfma_f32_32x32x16_bf16 v[98:113], v[98:101], v[114:117], 0
	s_waitcnt lgkmcnt(0)
	v_mfma_f32_32x32x16_bf16 v[98:113], v[118:121], v[130:133], v[98:113]
	ds_read_b64_tr_b16 v[118:119], v143 offset:3584
	ds_read_b64_tr_b16 v[120:121], v143 offset:7680
	ds_read_b64_tr_b16 v[144:145], v143 offset:11776
	ds_read_b64_tr_b16 v[146:147], v143 offset:15872
	s_waitcnt lgkmcnt(2)
	v_mfma_f32_32x32x16_bf16 v[114:129], v[118:121], v[114:117], 0
	s_waitcnt lgkmcnt(0)
	v_mfma_f32_32x32x16_bf16 v[114:129], v[144:147], v[130:133], v[114:129]
	s_and_saveexec_b64 s[2:3], vcc
	s_mov_b32 s45, s18
	s_mov_b32 s47, s19
	s_movk_i32 s48, 0xc0
	s_mov_b32 s39, 0x20000
	s_mov_b32 s40, 0x28000
	s_mov_b32 s41, 0x30000
	s_mov_b32 s42, 0x38000
	s_mov_b32 s43, 0x60000
	s_cbranch_execz .LBB0_594
	s_lshl_b32 s0, s0, 2
	s_add_i32 s0, s0, 0
	v_lshl_add_u32 v130, v139, 3, s0
	v_add_u32_e32 v130, 0x20000, v130
	v_add_f32_e32 v139, v0, v141
	ds_write_b64 v130, v[138:139]

; #define LAS __attribute__((address_space(3)))
; __device__ __forceinline__ void small_gemm_res(LAS unsigned char* lds, const bf16_t* A, const bf16_t* Bt, int K, int unit, bf16_t* XB, float* SS, float sc) {
;     int tid = threadIdx.x; asm volatile("" : "+v"(tid));
;     const int wave = __builtin_amdgcn_readfirstlane(tid >> 6), lane = tid & 63, li = lane & 15, g4 = lane >> 4;
;     const int ux = unit & 7, ur = unit >> 3;
;     const int ct = 2 * ux + (ur & 1), rt = ur >> 1, row0 = TP + 32 * rt, col0 = 64 * ct;
;     const int KS = K >> 8;
;     const int row = tid >> 4, c4 = (tid & 15) * 4;
;     const size_t off = (size_t)(row0 + row) * D + col0 + c4;
;     const u32x2 xw = *(const u32x2*)(XB + off);
;     f32x4 acc[2][4];
; #pragma unroll
;     for (int m = 0; m < 2; ++m)
; #pragma unroll
;         for (int t = 0; t < 4; ++t) acc[m][t] = (f32x4){0.f, 0.f, 0.f, 0.f};
;     const bf16_t* ap = A + (size_t)(row0 + li) * K + 8 * g4 + 32 * wave * KS;
;     const bf16_t* bp = Bt + (size_t)(col0 + li) * K + 8 * g4 + 32 * wave * KS;
; #pragma unroll 6
;     for (int ks = 0; ks < KS; ++ks) {
;         const bf16x8 a0 = *(const bf16x8*)(ap + 32 * ks), a1 = *(const bf16x8*)(ap + (size_t)16 * K + 32 * ks);
; #pragma unroll
;         for (int t = 0; t < 4; ++t) { const bf16x8 b = *(const bf16x8*)(bp + (size_t)16 * t * K + 32 * ks);
;             acc[0][t] = __builtin_amdgcn_mfma_f32_16x16x32_bf16(b, a0, acc[0][t], 0, 0, 0); acc[1][t] = __builtin_amdgcn_mfma_f32_16x16x32_bf16(b, a1, acc[1][t], 0, 0, 0); }
;     }
.LBB0_664:
	s_lshl_b32 s6, s17, 1
	v_mov_b32_e32 v4, v208
	s_and_b32 s28, s6, 14
	s_andn2_b32 s6, s6, 31
	s_addk_i32 s6, 0x4000
	v_ashrrev_i32_e32 v59, 4, v4
	v_add_u32_e32 v34, s6, v59
	s_bfe_u32 s29, s17, 0x10003
	v_ashrrev_i32_e32 v35, 31, v34
	s_or_b32 s30, s28, s29
	s_waitcnt lgkmcnt(0)
	v_lshlrev_b64 v[2:3], 11, v[34:35]
	v_and_b32_e32 v58, 15, v4
	v_lshl_add_u64 v[2:3], s[8:9], 0, v[2:3]
	s_lshl_b32 s62, s30, 7
	v_lshl_add_u64 v[2:3], v[2:3], 0, s[62:63]
	v_lshlrev_b32_e32 v0, 3, v58
	v_lshl_add_u64 v[36:37], v[2:3], 0, v[0:1]
	global_load_dwordx2 v[38:39], v[36:37], off
	v_lshl_or_b32 v0, s30, 6, v58
	v_mul_u32_u24_e32 v0, s7, v0
	s_and_b32 s6, s15, 0xffffffe0
	v_readfirstlane_b32 s28, v4
	v_bfe_u32 v4, v4, 4, 2
	v_lshlrev_b32_e32 v0, 1, v0
	v_lshl_add_u64 v[2:3], s[12:13], 0, v[0:1]
	v_lshlrev_b32_e32 v40, 4, v4
	v_mov_b32_e32 v41, v1
	s_addk_i32 s6, 0x4000
	v_lshl_add_u64 v[42:43], v[2:3], 0, v[40:41]
	v_lshl_add_u64 v[2:3], v[40:41], 0, v[0:1]
	v_or_b32_e32 v0, s6, v58
	v_lshl_add_u64 v[44:45], s[2:3], 0, v[2:3]
	v_lshl_add_u64 v[46:47], s[4:5], 0, v[2:3]
	v_lshl_add_u64 v[48:49], s[26:27], 0, v[2:3]
	v_lshl_or_b32 v2, v0, 1, 32
	s_ashr_i32 s31, s28, 1
	v_ashrrev_i32_e32 v4, 31, v0
	v_mad_u64_u32 v[2:3], s[34:35], s7, v2, v[40:41]
	s_andn2_b32 s31, s31, 31
	v_mad_i32_i24 v3, s7, v4, v3
	s_mul_i32 s28, s31, s14
	v_lshl_add_u64 v[50:51], s[22:23], 0, v[2:3]
	v_mad_i64_i32 v[2:3], s[34:35], s16, v0, v[40:41]
	s_ashr_i32 s29, s28, 31
	v_lshl_add_u64 v[52:53], s[22:23], 0, v[2:3]
	v_mov_b32_e32 v2, 0
	v_lshlrev_b32_e32 v60, 2, v58
	s_lshl_b64 s[28:29], s[28:29], 1
	s_mov_b32 s34, s14
	v_mov_b32_e32 v3, v2
	v_mov_b32_e32 v4, v2
	v_mov_b32_e32 v5, v2
	v_mov_b32_e32 v6, v2
	v_mov_b32_e32 v7, v2
	v_mov_b32_e32 v8, v2
	v_mov_b32_e32 v9, v2
	v_mov_b32_e32 v10, v2
	v_mov_b32_e32 v11, v2
	v_mov_b32_e32 v12, v2
	v_mov_b32_e32 v13, v2
	v_mov_b32_e32 v14, v2
	v_mov_b32_e32 v15, v2
	v_mov_b32_e32 v16, v2
	v_mov_b32_e32 v17, v2
	v_mov_b32_e32 v18, v2
	v_mov_b32_e32 v19, v2
	v_mov_b32_e32 v20, v2
	v_mov_b32_e32 v21, v2
	v_mov_b32_e32 v22, v2
	v_mov_b32_e32 v23, v2
	v_mov_b32_e32 v24, v2
	v_mov_b32_e32 v25, v2
	v_mov_b32_e32 v26, v2
	v_mov_b32_e32 v27, v2
	v_mov_b32_e32 v28, v2
	v_mov_b32_e32 v29, v2
	v_mov_b32_e32 v30, v2
	v_mov_b32_e32 v31, v2
	v_mov_b32_e32 v32, v2
	v_mov_b32_e32 v33, v2
	s_cmp_eq_u32 s34, 11
	s_cbranch_scc1 .Lsgr_k11
	s_cmp_eq_u32 s34, 4
	s_cbranch_scc1 .Lsgr_k4
.LBB0_665:
	v_lshl_add_u64 v[70:71], v[42:43], 0, s[28:29]
	flat_load_dwordx4 v[70:73], v[70:71]
	v_lshl_add_u64 v[62:63], v[52:53], 0, s[28:29]
	v_lshl_add_u64 v[66:67], v[50:51], 0, s[28:29]
	flat_load_dwordx4 v[62:65], v[62:63]
	s_add_i32 s34, s34, -1
	flat_load_dwordx4 v[66:69], v[66:67]
	v_lshl_add_u64 v[42:43], v[42:43], 0, 64
	v_lshl_add_u64 v[50:51], v[50:51], 0, 64
	v_lshl_add_u64 v[52:53], v[52:53], 0, 64
	s_cmp_eq_u32 s34, 0
	s_waitcnt vmcnt(0) lgkmcnt(0)
	v_mfma_f32_16x16x32_bf16 v[30:33], v[70:73], v[62:65], v[30:33]
	v_mfma_f32_16x16x32_bf16 v[14:17], v[70:73], v[66:69], v[14:17]
	v_lshl_add_u64 v[70:71], v[48:49], 0, s[28:29]
	flat_load_dwordx4 v[70:73], v[70:71]
	v_lshl_add_u64 v[48:49], v[48:49], 0, 64
	s_waitcnt vmcnt(0) lgkmcnt(0)
	v_mfma_f32_16x16x32_bf16 v[26:29], v[70:73], v[62:65], v[26:29]
	v_mfma_f32_16x16x32_bf16 v[10:13], v[70:73], v[66:69], v[10:13]
	v_lshl_add_u64 v[70:71], v[46:47], 0, s[28:29]
	flat_load_dwordx4 v[70:73], v[70:71]
	v_lshl_add_u64 v[46:47], v[46:47], 0, 64
	s_waitcnt vmcnt(0) lgkmcnt(0)
	v_mfma_f32_16x16x32_bf16 v[22:25], v[70:73], v[62:65], v[22:25]
	v_mfma_f32_16x16x32_bf16 v[6:9], v[70:73], v[66:69], v[6:9]
	v_lshl_add_u64 v[70:71], v[44:45], 0, s[28:29]
	flat_load_dwordx4 v[70:73], v[70:71]
	v_lshl_add_u64 v[44:45], v[44:45], 0, 64
	s_waitcnt vmcnt(0) lgkmcnt(0)
	v_mfma_f32_16x16x32_bf16 v[18:21], v[70:73], v[62:65], v[18:21]
	v_mfma_f32_16x16x32_bf16 v[2:5], v[70:73], v[66:69], v[2:5]
	s_cbranch_scc0 .LBB0_665
	s_branch .Lsgr_done
.Lsgr_k11:
	v_lshl_add_u64 v[52:53], v[52:53], 0, s[28:29]
	v_lshl_add_u64 v[50:51], v[50:51], 0, s[28:29]
	v_lshl_add_u64 v[42:43], v[42:43], 0, s[28:29]
	v_lshl_add_u64 v[48:49], v[48:49], 0, s[28:29]
	v_lshl_add_u64 v[46:47], v[46:47], 0, s[28:29]
	v_lshl_add_u64 v[44:45], v[44:45], 0, s[28:29]
	global_load_dwordx4 v[62:65], v[52:53], off
	global_load_dwordx4 v[66:69], v[50:51], off
	global_load_dwordx4 v[70:73], v[42:43], off
	global_load_dwordx4 v[74:77], v[48:49], off
	global_load_dwordx4 v[78:81], v[46:47], off
	global_load_dwordx4 v[82:85], v[44:45], off
	global_load_dwordx4 v[86:89], v[52:53], off offset:64
	global_load_dwordx4 v[90:93], v[50:51], off offset:64
	global_load_dwordx4 v[94:97], v[42:43], off offset:64
	global_load_dwordx4 v[98:101], v[48:49], off offset:64
	global_load_dwordx4 v[102:105], v[46:47], off offset:64
	global_load_dwordx4 v[106:109], v[44:45], off offset:64
	global_load_dwordx4 v[110:113], v[52:53], off offset:128
	global_load_dwordx4 v[114:117], v[50:51], off offset:128
	global_load_dwordx4 v[118:121], v[42:43], off offset:128
	global_load_dwordx4 v[122:125], v[48:49], off offset:128
	global_load_dwordx4 v[126:129], v[46:47], off offset:128
	s_waitcnt vmcnt(14)
	v_mfma_f32_16x16x32_bf16 v[30:33], v[70:73], v[62:65], v[30:33]
	v_mfma_f32_16x16x32_bf16 v[14:17], v[70:73], v[66:69], v[14:17]
	s_waitcnt vmcnt(13)
	v_mfma_f32_16x16x32_bf16 v[26:29], v[74:77], v[62:65], v[26:29]
	v_mfma_f32_16x16x32_bf16 v[10:13], v[74:77], v[66:69], v[10:13]
	s_waitcnt vmcnt(12)
	v_mfma_f32_16x16x32_bf16 v[22:25], v[78:81], v[62:65], v[22:25]
	v_mfma_f32_16x16x32_bf16 v[6:9], v[78:81], v[66:69], v[6:9]
	s_waitcnt vmcnt(11)
; __device__ __forceinline__ void small_gemm_res(LAS unsigned char* lds, const bf16_t* A, const bf16_t* Bt, int K, int unit, bf16_t* XB, float* SS, float sc) {
;     ...
; #pragma unroll 6
;     for (int ks = 0; ks < KS; ++ks) {
;         const bf16x8 a0 = *(const bf16x8*)(ap + 32 * ks), a1 = *(const bf16x8*)(ap + (size_t)16 * K + 32 * ks);
; #pragma unroll
;         for (int t = 0; t < 4; ++t) { const bf16x8 b = *(const bf16x8*)(bp + (size_t)16 * t * K + 32 * ks);
;             acc[0][t] = __builtin_amdgcn_mfma_f32_16x16x32_bf16(b, a0, acc[0][t], 0, 0, 0); acc[1][t] = __builtin_amdgcn_mfma_f32_16x16x32_bf16(b, a1, acc[1][t], 0, 0, 0); }
;     }
	v_mfma_f32_16x16x32_bf16 v[18:21], v[82:85], v[62:65], v[18:21]
	v_mfma_f32_16x16x32_bf16 v[2:5], v[82:85], v[66:69], v[2:5]
	global_load_dwordx4 v[62:65], v[44:45], off offset:128
	global_load_dwordx4 v[66:69], v[52:53], off offset:192
	global_load_dwordx4 v[70:73], v[50:51], off offset:192
	global_load_dwordx4 v[74:77], v[42:43], off offset:192
	global_load_dwordx4 v[78:81], v[48:49], off offset:192
	global_load_dwordx4 v[82:85], v[46:47], off offset:192
	s_waitcnt vmcnt(14)
	v_mfma_f32_16x16x32_bf16 v[30:33], v[94:97], v[86:89], v[30:33]
	v_mfma_f32_16x16x32_bf16 v[14:17], v[94:97], v[90:93], v[14:17]
	s_waitcnt vmcnt(13)
	v_mfma_f32_16x16x32_bf16 v[26:29], v[98:101], v[86:89], v[26:29]
	v_mfma_f32_16x16x32_bf16 v[10:13], v[98:101], v[90:93], v[10:13]
	s_waitcnt vmcnt(12)
	v_mfma_f32_16x16x32_bf16 v[22:25], v[102:105], v[86:89], v[22:25]
	v_mfma_f32_16x16x32_bf16 v[6:9], v[102:105], v[90:93], v[6:9]
	s_waitcnt vmcnt(11)
	v_mfma_f32_16x16x32_bf16 v[18:21], v[106:109], v[86:89], v[18:21]
	v_mfma_f32_16x16x32_bf16 v[2:5], v[106:109], v[90:93], v[2:5]
	global_load_dwordx4 v[86:89], v[44:45], off offset:192
	global_load_dwordx4 v[90:93], v[52:53], off offset:256
	global_load_dwordx4 v[94:97], v[50:51], off offset:256
	global_load_dwordx4 v[98:101], v[42:43], off offset:256
	global_load_dwordx4 v[102:105], v[48:49], off offset:256
	global_load_dwordx4 v[106:109], v[46:47], off offset:256
	s_waitcnt vmcnt(14)
	v_mfma_f32_16x16x32_bf16 v[30:33], v[118:121], v[110:113], v[30:33]
	v_mfma_f32_16x16x32_bf16 v[14:17], v[118:121], v[114:117], v[14:17]
	s_waitcnt vmcnt(13)
	v_mfma_f32_16x16x32_bf16 v[26:29], v[122:125], v[110:113], v[26:29]
	v_mfma_f32_16x16x32_bf16 v[10:13], v[122:125], v[114:117], v[10:13]
	s_waitcnt vmcnt(12)
	v_mfma_f32_16x16x32_bf16 v[22:25], v[126:129], v[110:113], v[22:25]
	v_mfma_f32_16x16x32_bf16 v[6:9], v[126:129], v[114:117], v[6:9]
	s_waitcnt vmcnt(11)
	v_mfma_f32_16x16x32_bf16 v[18:21], v[62:65], v[110:113], v[18:21]
	v_mfma_f32_16x16x32_bf16 v[2:5], v[62:65], v[114:117], v[2:5]
	global_load_dwordx4 v[110:113], v[44:45], off offset:256
	global_load_dwordx4 v[114:117], v[52:53], off offset:320
	global_load_dwordx4 v[118:121], v[50:51], off offset:320
	global_load_dwordx4 v[122:125], v[42:43], off offset:320
	global_load_dwordx4 v[126:129], v[48:49], off offset:320
	global_load_dwordx4 v[62:65], v[46:47], off offset:320
	s_waitcnt vmcnt(14)
	v_mfma_f32_16x16x32_bf16 v[30:33], v[74:77], v[66:69], v[30:33]
	v_mfma_f32_16x16x32_bf16 v[14:17], v[74:77], v[70:73], v[14:17]
	s_waitcnt vmcnt(13)
	v_mfma_f32_16x16x32_bf16 v[26:29], v[78:81], v[66:69], v[26:29]
	v_mfma_f32_16x16x32_bf16 v[10:13], v[78:81], v[70:73], v[10:13]
	s_waitcnt vmcnt(12)
	v_mfma_f32_16x16x32_bf16 v[22:25], v[82:85], v[66:69], v[22:25]
	v_mfma_f32_16x16x32_bf16 v[6:9], v[82:85], v[70:73], v[6:9]
	s_waitcnt vmcnt(11)
	v_mfma_f32_16x16x32_bf16 v[18:21], v[86:89], v[66:69], v[18:21]
	v_mfma_f32_16x16x32_bf16 v[2:5], v[86:89], v[70:73], v[2:5]
	global_load_dwordx4 v[66:69], v[44:45], off offset:320
	global_load_dwordx4 v[70:73], v[52:53], off offset:384
	global_load_dwordx4 v[74:77], v[50:51], off offset:384
	global_load_dwordx4 v[78:81], v[42:43], off offset:384
	global_load_dwordx4 v[82:85], v[48:49], off offset:384
	global_load_dwordx4 v[86:89], v[46:47], off offset:384
	s_waitcnt vmcnt(14)
	v_mfma_f32_16x16x32_bf16 v[30:33], v[98:101], v[90:93], v[30:33]
	v_mfma_f32_16x16x32_bf16 v[14:17], v[98:101], v[94:97], v[14:17]
	s_waitcnt vmcnt(13)
	v_mfma_f32_16x16x32_bf16 v[26:29], v[102:105], v[90:93], v[26:29]
	v_mfma_f32_16x16x32_bf16 v[10:13], v[102:105], v[94:97], v[10:13]
	s_waitcnt vmcnt(12)
	v_mfma_f32_16x16x32_bf16 v[22:25], v[106:109], v[90:93], v[22:25]
	v_mfma_f32_16x16x32_bf16 v[6:9], v[106:109], v[94:97], v[6:9]
	s_waitcnt vmcnt(11)
	v_mfma_f32_16x16x32_bf16 v[18:21], v[110:113], v[90:93], v[18:21]
	v_mfma_f32_16x16x32_bf16 v[2:5], v[110:113], v[94:97], v[2:5]
	global_load_dwordx4 v[90:93], v[44:45], off offset:384
	global_load_dwordx4 v[94:97], v[52:53], off offset:448
	global_load_dwordx4 v[98:101], v[50:51], off offset:448
	global_load_dwordx4 v[102:105], v[42:43], off offset:448
	global_load_dwordx4 v[106:109], v[48:49], off offset:448
	global_load_dwordx4 v[110:113], v[46:47], off offset:448
	s_waitcnt vmcnt(14)
	v_mfma_f32_16x16x32_bf16 v[30:33], v[122:125], v[114:117], v[30:33]
	v_mfma_f32_16x16x32_bf16 v[14:17], v[122:125], v[118:121], v[14:17]
	s_waitcnt vmcnt(13)
	v_mfma_f32_16x16x32_bf16 v[26:29], v[126:129], v[114:117], v[26:29]
	v_mfma_f32_16x16x32_bf16 v[10:13], v[126:129], v[118:121], v[10:13]
	s_waitcnt vmcnt(12)
	v_mfma_f32_16x16x32_bf16 v[22:25], v[62:65], v[114:117], v[22:25]
	v_mfma_f32_16x16x32_bf16 v[6:9], v[62:65], v[118:121], v[6:9]
	s_waitcnt vmcnt(11)
	v_mfma_f32_16x16x32_bf16 v[18:21], v[66:69], v[114:117], v[18:21]
	v_mfma_f32_16x16x32_bf16 v[2:5], v[66:69], v[118:121], v[2:5]
	global_load_dwordx4 v[114:117], v[44:45], off offset:448
	global_load_dwordx4 v[118:121], v[52:53], off offset:512
	global_load_dwordx4 v[122:125], v[50:51], off offset:512
	global_load_dwordx4 v[126:129], v[42:43], off offset:512
	global_load_dwordx4 v[62:65], v[48:49], off offset:512
	global_load_dwordx4 v[66:69], v[46:47], off offset:512
	s_waitcnt vmcnt(14)
	v_mfma_f32_16x16x32_bf16 v[30:33], v[78:81], v[70:73], v[30:33]
	v_mfma_f32_16x16x32_bf16 v[14:17], v[78:81], v[74:77], v[14:17]
	s_waitcnt vmcnt(13)
	v_mfma_f32_16x16x32_bf16 v[26:29], v[82:85], v[70:73], v[26:29]
	v_mfma_f32_16x16x32_bf16 v[10:13], v[82:85], v[74:77], v[10:13]
	s_waitcnt vmcnt(12)
	v_mfma_f32_16x16x32_bf16 v[22:25], v[86:89], v[70:73], v[22:25]
	v_mfma_f32_16x16x32_bf16 v[6:9], v[86:89], v[74:77], v[6:9]
	s_waitcnt vmcnt(11)
; __device__ __forceinline__ void small_gemm_res(LAS unsigned char* lds, const bf16_t* A, const bf16_t* Bt, int K, int unit, bf16_t* XB, float* SS, float sc) {
;     ...
; #pragma unroll 6
;     for (int ks = 0; ks < KS; ++ks) {
;         const bf16x8 a0 = *(const bf16x8*)(ap + 32 * ks), a1 = *(const bf16x8*)(ap + (size_t)16 * K + 32 * ks);
; #pragma unroll
;         for (int t = 0; t < 4; ++t) { const bf16x8 b = *(const bf16x8*)(bp + (size_t)16 * t * K + 32 * ks);
;             acc[0][t] = __builtin_amdgcn_mfma_f32_16x16x32_bf16(b, a0, acc[0][t], 0, 0, 0); acc[1][t] = __builtin_amdgcn_mfma_f32_16x16x32_bf16(b, a1, acc[1][t], 0, 0, 0); }
;     }
	v_mfma_f32_16x16x32_bf16 v[18:21], v[90:93], v[70:73], v[18:21]
	v_mfma_f32_16x16x32_bf16 v[2:5], v[90:93], v[74:77], v[2:5]
	global_load_dwordx4 v[70:73], v[44:45], off offset:512
	global_load_dwordx4 v[74:77], v[52:53], off offset:576
	global_load_dwordx4 v[78:81], v[50:51], off offset:576
	global_load_dwordx4 v[82:85], v[42:43], off offset:576
	global_load_dwordx4 v[86:89], v[48:49], off offset:576
	global_load_dwordx4 v[90:93], v[46:47], off offset:576
	s_waitcnt vmcnt(14)
	v_mfma_f32_16x16x32_bf16 v[30:33], v[102:105], v[94:97], v[30:33]
	v_mfma_f32_16x16x32_bf16 v[14:17], v[102:105], v[98:101], v[14:17]
	s_waitcnt vmcnt(13)
	v_mfma_f32_16x16x32_bf16 v[26:29], v[106:109], v[94:97], v[26:29]
	v_mfma_f32_16x16x32_bf16 v[10:13], v[106:109], v[98:101], v[10:13]
	s_waitcnt vmcnt(12)
	v_mfma_f32_16x16x32_bf16 v[22:25], v[110:113], v[94:97], v[22:25]
	v_mfma_f32_16x16x32_bf16 v[6:9], v[110:113], v[98:101], v[6:9]
	s_waitcnt vmcnt(11)
	v_mfma_f32_16x16x32_bf16 v[18:21], v[114:117], v[94:97], v[18:21]
	v_mfma_f32_16x16x32_bf16 v[2:5], v[114:117], v[98:101], v[2:5]
	global_load_dwordx4 v[94:97], v[44:45], off offset:576
	global_load_dwordx4 v[98:101], v[52:53], off offset:640
	global_load_dwordx4 v[102:105], v[50:51], off offset:640
	global_load_dwordx4 v[106:109], v[42:43], off offset:640
	global_load_dwordx4 v[110:113], v[48:49], off offset:640
	global_load_dwordx4 v[114:117], v[46:47], off offset:640
	s_waitcnt vmcnt(14)
	v_mfma_f32_16x16x32_bf16 v[30:33], v[126:129], v[118:121], v[30:33]
	v_mfma_f32_16x16x32_bf16 v[14:17], v[126:129], v[122:125], v[14:17]
	s_waitcnt vmcnt(13)
	v_mfma_f32_16x16x32_bf16 v[26:29], v[62:65], v[118:121], v[26:29]
	v_mfma_f32_16x16x32_bf16 v[10:13], v[62:65], v[122:125], v[10:13]
	s_waitcnt vmcnt(12)
	v_mfma_f32_16x16x32_bf16 v[22:25], v[66:69], v[118:121], v[22:25]
	v_mfma_f32_16x16x32_bf16 v[6:9], v[66:69], v[122:125], v[6:9]
	s_waitcnt vmcnt(11)
	v_mfma_f32_16x16x32_bf16 v[18:21], v[70:73], v[118:121], v[18:21]
	v_mfma_f32_16x16x32_bf16 v[2:5], v[70:73], v[122:125], v[2:5]
	global_load_dwordx4 v[118:121], v[44:45], off offset:640
	s_waitcnt vmcnt(9)
	v_mfma_f32_16x16x32_bf16 v[30:33], v[82:85], v[74:77], v[30:33]
	v_mfma_f32_16x16x32_bf16 v[14:17], v[82:85], v[78:81], v[14:17]
	s_waitcnt vmcnt(8)
	v_mfma_f32_16x16x32_bf16 v[26:29], v[86:89], v[74:77], v[26:29]
	v_mfma_f32_16x16x32_bf16 v[10:13], v[86:89], v[78:81], v[10:13]
	s_waitcnt vmcnt(7)
	v_mfma_f32_16x16x32_bf16 v[22:25], v[90:93], v[74:77], v[22:25]
	v_mfma_f32_16x16x32_bf16 v[6:9], v[90:93], v[78:81], v[6:9]
	s_waitcnt vmcnt(6)
	v_mfma_f32_16x16x32_bf16 v[18:21], v[94:97], v[74:77], v[18:21]
	v_mfma_f32_16x16x32_bf16 v[2:5], v[94:97], v[78:81], v[2:5]
	s_waitcnt vmcnt(3)
	v_mfma_f32_16x16x32_bf16 v[30:33], v[106:109], v[98:101], v[30:33]
	v_mfma_f32_16x16x32_bf16 v[14:17], v[106:109], v[102:105], v[14:17]
	s_waitcnt vmcnt(2)
	v_mfma_f32_16x16x32_bf16 v[26:29], v[110:113], v[98:101], v[26:29]
	v_mfma_f32_16x16x32_bf16 v[10:13], v[110:113], v[102:105], v[10:13]
	s_waitcnt vmcnt(1)
	v_mfma_f32_16x16x32_bf16 v[22:25], v[114:117], v[98:101], v[22:25]
	v_mfma_f32_16x16x32_bf16 v[6:9], v[114:117], v[102:105], v[6:9]
	s_waitcnt vmcnt(0)
	v_mfma_f32_16x16x32_bf16 v[18:21], v[118:121], v[98:101], v[18:21]
	v_mfma_f32_16x16x32_bf16 v[2:5], v[118:121], v[102:105], v[2:5]
	s_branch .Lsgr_done
; #define LAS __attribute__((address_space(3)))
; __device__ __forceinline__ unsigned cvt_pk_bf16(float lo, float hi) { unsigned r; asm("v_cvt_pk_bf16_f32 %0, %1, %2" : "=v"(r) : "v"(lo), "v"(hi)); return r; }
; __device__ __forceinline__ float bf_lo(unsigned w) { return __uint_as_float(w << 16); }
; __device__ __forceinline__ float bf_hi(unsigned w) { return __uint_as_float(w & 0xffff0000u); }
; __device__ __forceinline__ void small_gemm_res(LAS unsigned char* lds, const bf16_t* A, const bf16_t* Bt, int K, int unit, bf16_t* XB, float* SS, float sc) {
;     ...
; #pragma unroll 6
;     for (int ks = 0; ks < KS; ++ks) {
;         const bf16x8 a0 = *(const bf16x8*)(ap + 32 * ks), a1 = *(const bf16x8*)(ap + (size_t)16 * K + 32 * ks);
; #pragma unroll
;         for (int t = 0; t < 4; ++t) { const bf16x8 b = *(const bf16x8*)(bp + (size_t)16 * t * K + 32 * ks);
;             acc[0][t] = __builtin_amdgcn_mfma_f32_16x16x32_bf16(b, a0, acc[0][t], 0, 0, 0); acc[1][t] = __builtin_amdgcn_mfma_f32_16x16x32_bf16(b, a1, acc[1][t], 0, 0, 0); }
;     }
;     LAS float* red = (LAS float*)lds;
; #pragma unroll
;     for (int m = 0; m < 2; ++m)
; #pragma unroll
;         for (int t = 0; t < 4; ++t) *(LAS f32x4*)(red + (wave * 32 + 16 * m + li) * 64 + 16 * t + 4 * g4) = acc[m][t];
;     __syncthreads();
;     f32x4 sum = *(LAS f32x4*)(red + row * 64 + c4);
; #pragma unroll
;     for (int w = 1; w < 8; ++w) sum += *(LAS f32x4*)(red + (w * 32 + row) * 64 + c4);
;     f32x4 x = (f32x4){bf_lo(xw.x), bf_hi(xw.x), bf_lo(xw.y), bf_hi(xw.y)}; x += sum * sc;
;     u32x2 w; w.x = cvt_pk_bf16(x[0], x[1]); w.y = cvt_pk_bf16(x[2], x[3]); *(u32x2*)(XB + off) = w;
;     float ss = (x[0] * x[0] + x[1] * x[1]) + (x[2] * x[2] + x[3] * x[3]);
;     ss += __shfl_xor(ss, 1); ss += __shfl_xor(ss, 2); ss += __shfl_xor(ss, 4); ss += __shfl_xor(ss, 8);
;     if ((tid & 15) == 0) SS[(size_t)(row0 + row) * 16 + ct] = ss;
.Lsgr_k4:
	v_lshl_add_u64 v[52:53], v[52:53], 0, s[28:29]
	v_lshl_add_u64 v[50:51], v[50:51], 0, s[28:29]
	v_lshl_add_u64 v[42:43], v[42:43], 0, s[28:29]
	v_lshl_add_u64 v[48:49], v[48:49], 0, s[28:29]
	v_lshl_add_u64 v[46:47], v[46:47], 0, s[28:29]
	v_lshl_add_u64 v[44:45], v[44:45], 0, s[28:29]
	global_load_dwordx4 v[62:65], v[52:53], off
	global_load_dwordx4 v[66:69], v[50:51], off
	global_load_dwordx4 v[70:73], v[42:43], off
	global_load_dwordx4 v[74:77], v[48:49], off
	global_load_dwordx4 v[78:81], v[46:47], off
	global_load_dwordx4 v[82:85], v[44:45], off
	global_load_dwordx4 v[86:89], v[52:53], off offset:64
	global_load_dwordx4 v[90:93], v[50:51], off offset:64
	global_load_dwordx4 v[94:97], v[42:43], off offset:64
	global_load_dwordx4 v[98:101], v[48:49], off offset:64
	global_load_dwordx4 v[102:105], v[46:47], off offset:64
	global_load_dwordx4 v[106:109], v[44:45], off offset:64
	global_load_dwordx4 v[110:113], v[52:53], off offset:128
	global_load_dwordx4 v[114:117], v[50:51], off offset:128
	global_load_dwordx4 v[118:121], v[42:43], off offset:128
	global_load_dwordx4 v[122:125], v[48:49], off offset:128
	global_load_dwordx4 v[126:129], v[46:47], off offset:128
	s_waitcnt vmcnt(14)
	v_mfma_f32_16x16x32_bf16 v[30:33], v[70:73], v[62:65], v[30:33]
	v_mfma_f32_16x16x32_bf16 v[14:17], v[70:73], v[66:69], v[14:17]
	s_waitcnt vmcnt(13)
	v_mfma_f32_16x16x32_bf16 v[26:29], v[74:77], v[62:65], v[26:29]
	v_mfma_f32_16x16x32_bf16 v[10:13], v[74:77], v[66:69], v[10:13]
	s_waitcnt vmcnt(12)
	v_mfma_f32_16x16x32_bf16 v[22:25], v[78:81], v[62:65], v[22:25]
	v_mfma_f32_16x16x32_bf16 v[6:9], v[78:81], v[66:69], v[6:9]
	s_waitcnt vmcnt(11)
	v_mfma_f32_16x16x32_bf16 v[18:21], v[82:85], v[62:65], v[18:21]
	v_mfma_f32_16x16x32_bf16 v[2:5], v[82:85], v[66:69], v[2:5]
	global_load_dwordx4 v[62:65], v[44:45], off offset:128
	global_load_dwordx4 v[66:69], v[52:53], off offset:192
	global_load_dwordx4 v[70:73], v[50:51], off offset:192
	global_load_dwordx4 v[74:77], v[42:43], off offset:192
	global_load_dwordx4 v[78:81], v[48:49], off offset:192
	global_load_dwordx4 v[82:85], v[46:47], off offset:192
	s_waitcnt vmcnt(14)
	v_mfma_f32_16x16x32_bf16 v[30:33], v[94:97], v[86:89], v[30:33]
	v_mfma_f32_16x16x32_bf16 v[14:17], v[94:97], v[90:93], v[14:17]
	s_waitcnt vmcnt(13)
	v_mfma_f32_16x16x32_bf16 v[26:29], v[98:101], v[86:89], v[26:29]
	v_mfma_f32_16x16x32_bf16 v[10:13], v[98:101], v[90:93], v[10:13]
	s_waitcnt vmcnt(12)
	v_mfma_f32_16x16x32_bf16 v[22:25], v[102:105], v[86:89], v[22:25]
	v_mfma_f32_16x16x32_bf16 v[6:9], v[102:105], v[90:93], v[6:9]
	s_waitcnt vmcnt(11)
	v_mfma_f32_16x16x32_bf16 v[18:21], v[106:109], v[86:89], v[18:21]
	v_mfma_f32_16x16x32_bf16 v[2:5], v[106:109], v[90:93], v[2:5]
	global_load_dwordx4 v[86:89], v[44:45], off offset:192
	s_waitcnt vmcnt(9)
	v_mfma_f32_16x16x32_bf16 v[30:33], v[118:121], v[110:113], v[30:33]
	v_mfma_f32_16x16x32_bf16 v[14:17], v[118:121], v[114:117], v[14:17]
	s_waitcnt vmcnt(8)
	v_mfma_f32_16x16x32_bf16 v[26:29], v[122:125], v[110:113], v[26:29]
	v_mfma_f32_16x16x32_bf16 v[10:13], v[122:125], v[114:117], v[10:13]
	s_waitcnt vmcnt(7)
	v_mfma_f32_16x16x32_bf16 v[22:25], v[126:129], v[110:113], v[22:25]
	v_mfma_f32_16x16x32_bf16 v[6:9], v[126:129], v[114:117], v[6:9]
	s_waitcnt vmcnt(6)
	v_mfma_f32_16x16x32_bf16 v[18:21], v[62:65], v[110:113], v[18:21]
	v_mfma_f32_16x16x32_bf16 v[2:5], v[62:65], v[114:117], v[2:5]
	s_waitcnt vmcnt(3)
	v_mfma_f32_16x16x32_bf16 v[30:33], v[74:77], v[66:69], v[30:33]
	v_mfma_f32_16x16x32_bf16 v[14:17], v[74:77], v[70:73], v[14:17]
	s_waitcnt vmcnt(2)
	v_mfma_f32_16x16x32_bf16 v[26:29], v[78:81], v[66:69], v[26:29]
	v_mfma_f32_16x16x32_bf16 v[10:13], v[78:81], v[70:73], v[10:13]
	s_waitcnt vmcnt(1)
	v_mfma_f32_16x16x32_bf16 v[22:25], v[82:85], v[66:69], v[22:25]
	v_mfma_f32_16x16x32_bf16 v[6:9], v[82:85], v[70:73], v[6:9]
	s_waitcnt vmcnt(0)
	v_mfma_f32_16x16x32_bf16 v[18:21], v[86:89], v[66:69], v[18:21]
	v_mfma_f32_16x16x32_bf16 v[2:5], v[86:89], v[70:73], v[2:5]
.Lsgr_done:
	s_nop 1
	v_or_b32_e32 v0, s31, v58
	v_lshlrev_b32_e32 v0, 8, v0
	v_add3_u32 v0, 0, v40, v0
	ds_write_b128 v0, v[30:33]
	ds_write_b128 v0, v[26:29] offset:64
	ds_write_b128 v0, v[22:25] offset:128
	ds_write_b128 v0, v[18:21] offset:192
	ds_write_b128 v0, v[14:17] offset:4096
	ds_write_b128 v0, v[10:13] offset:4160
	ds_write_b128 v0, v[6:9] offset:4224
	ds_write_b128 v0, v[2:5] offset:4288
	v_lshlrev_b32_e32 v0, 8, v59
	v_lshlrev_b32_e32 v2, 2, v60
	v_add3_u32 v0, 0, v0, v2
	s_waitcnt lgkmcnt(0)
	s_barrier
	ds_read_b128 v[2:5], v0
	ds_read_b128 v[6:9], v0 offset:8192
	ds_read_b128 v[10:13], v0 offset:16384
	ds_read_b128 v[14:17], v0 offset:24576
	v_cmp_eq_u32_e32 vcc, 0, v58
	s_waitcnt lgkmcnt(2)
	v_pk_add_f32 v[4:5], v[4:5], v[8:9]
	v_pk_add_f32 v[6:7], v[2:3], v[6:7]
	s_waitcnt lgkmcnt(1)
	v_pk_add_f32 v[8:9], v[4:5], v[12:13]
	ds_read_b128 v[2:5], v0 offset:32768
	v_pk_add_f32 v[6:7], v[6:7], v[10:11]
	s_waitcnt lgkmcnt(1)
	v_pk_add_f32 v[10:11], v[8:9], v[16:17]
	v_pk_add_f32 v[14:15], v[6:7], v[14:15]
	ds_read_b128 v[6:9], v0 offset:40960
	s_waitcnt lgkmcnt(1)
	v_pk_add_f32 v[16:17], v[10:11], v[4:5]
	ds_read_b128 v[10:13], v0 offset:49152
	v_pk_add_f32 v[14:15], v[14:15], v[2:3]
	ds_read_b128 v[2:5], v0 offset:57344
	s_waitcnt lgkmcnt(2)
	v_pk_add_f32 v[8:9], v[16:17], v[8:9]
	v_pk_add_f32 v[6:7], v[14:15], v[6:7]
	s_waitcnt lgkmcnt(1)
	v_pk_add_f32 v[8:9], v[8:9], v[12:13]
	v_pk_add_f32 v[6:7], v[6:7], v[10:11]
	s_waitcnt lgkmcnt(0)
	v_pk_add_f32 v[4:5], v[8:9], v[4:5]
	v_pk_add_f32 v[2:3], v[6:7], v[2:3]
	v_lshlrev_b32_e32 v6, 16, v38
	v_and_b32_e32 v7, 0xffff0000, v38
	v_lshlrev_b32_e32 v8, 16, v39
	v_and_b32_e32 v9, 0xffff0000, v39
	v_pk_fma_f32 v[4:5], s[0:1], v[4:5], v[8:9]
	v_pk_fma_f32 v[6:7], s[24:25], v[2:3], v[6:7]
	v_mul_f32_e32 v2, v5, v5
	v_mul_f32_e32 v0, v7, v7
	v_fmac_f32_e32 v0, v6, v6
	v_fmac_f32_e32 v2, v4, v4
	v_add_f32_e32 v0, v0, v2
	ds_bpermute_b32 v2, v54, v0
	v_cvt_pk_bf16_f32 v6, v6, v7
	v_cvt_pk_bf16_f32 v7, v4, v5
	flat_store_dwordx2 v[36:37], v[6:7]
	s_waitcnt lgkmcnt(0)
	v_add_f32_e32 v0, v0, v2
	ds_bpermute_b32 v2, v55, v0
	s_waitcnt lgkmcnt(0)
	v_add_f32_e32 v0, v0, v2
	ds_bpermute_b32 v2, v56, v0
	s_waitcnt lgkmcnt(0)
	v_add_f32_e32 v0, v0, v2
	ds_bpermute_b32 v2, v57, v0
	s_and_saveexec_b64 s[28:29], vcc
	s_cbranch_execz .LBB0_663
	s_waitcnt lgkmcnt(0)
	v_add_f32_e32 v0, v0, v2
	v_lshlrev_b64 v[2:3], 6, v[34:35]
	v_lshl_add_u64 v[2:3], s[10:11], 0, v[2:3]
	s_lshl_b32 s62, s30, 2
	v_lshl_add_u64 v[2:3], v[2:3], 0, s[62:63]
	flat_store_dword v[2:3], v0
	s_branch .LBB0_663

; #define LAS __attribute__((address_space(3)))
; __device__ __forceinline__ void k_frags(bf16x8 (&kf)[4], const bf16x8 (&kraw)[4], LAS unsigned char* kst, int lane) {
;     const int hi = lane >> 5, r = lane & 31;
; #pragma unroll
;     for (int i = 0; i < 4; ++i) *(LAS bf16x8*)(kst + koff_band((lane >> 3) + 8 * i, lane & 7)) = kraw[i];
; #pragma unroll
;     for (int d0 = 0; d0 < 4; ++d0) kf[d0] = *(const LAS bf16x8*)(kst + koff_band(r, 2 * d0 + hi));
; }
; __device__ __forceinline__ void attn_qk(AttnState& st, bf16x8 (&pf)[2], const bf16x8 (&kraw)[4], const bf16x8 (&qf)[4], int j, int qi, bool mask_hi,
;                                         LAS float* tab, float tconst, LAS unsigned char* kst, int lane) {
;     bf16x8 kf[4];
;     k_frags(kf, kraw, kst, lane);
;     attn_score(st, pf, kf, qf, j, qi, mask_hi, tab, tconst, lane);
; }
; __device__ __forceinline__ void attn_score(AttnState& st, bf16x8 (&pf)[2], const bf16x8 (&kf)[4], const bf16x8 (&qf)[4], int j, int qi, bool mask_hi,
;                                            LAS float* tab, float tconst, int lane) {
;     constexpr float C2 = 0.125f * LOG2E;
;     const int hi = lane >> 5;
;     f32x16 s;
; #pragma unroll
;     for (int e = 0; e < 16; ++e) s[e] = 0.f;
;     __builtin_amdgcn_s_setprio(1);
; #pragma unroll
;     for (int d0 = 0; d0 < 4; ++d0) s = __builtin_amdgcn_mfma_f32_32x32x16_bf16(kf[d0], qf[d0], s, 0, 0, 0);
;     __builtin_amdgcn_s_setprio(0);
; __device__ __forceinline__ void band_attn_p2(const Params& P, int l, int b, int c, int h, LAS unsigned char* wl, int lane_) {
;     ...
;     for (int j = jb0; j < 18; ++j) {
; #pragma unroll
;         for (int i = 0; i < 4; ++i) vc[i] = *(const bf16x8*)(zb + (size_t)(32 * j + 8 * i) * DIN + 1024);
;         if (j + 1 < 18) {
; #pragma unroll
;             for (int i = 0; i < 4; ++i) kn[i] = *(const bf16x8*)(zb + (size_t)(32 * (j + 1) + 8 * i) * DIN + 512);
;         }
;         bf16x8 kf[4], pf[2][2];
;         k_frags(kf, kc, kst, lane);
; #pragma unroll
;         for (int qb = 0; qb < 2; ++qb) attn_score(st[qb], pf[qb], kf, qf[qb], j, 32 * qb + r, false, tab, tconst, lane);
.LBB0_697:
	s_waitcnt vmcnt(8)
	ds_write_b128 v230, v[66:69] offset:6144
	ds_write_b128 v231, v[70:73] offset:6144
	ds_write_b128 v230, v[74:77] offset:8192
	ds_write_b128 v232, v[78:81] offset:6144
	ds_read_b128 v[182:185], v233 offset:6144
	ds_read_b128 v[178:181], v234 offset:6144
	ds_read_b128 v[174:177], v235 offset:6144
	ds_read_b128 v[170:173], v236 offset:6144
	s_cmp_lt_u32 s6, 12
	s_cselect_b64 s[0:1], -1, 0
	s_cmp_gt_u32 s6, 11
	s_setprio 1
	s_waitcnt lgkmcnt(3)
	v_mfma_f32_32x32x16_bf16 v[82:97], v[182:185], v[98:101], 0
	s_waitcnt lgkmcnt(2)
	v_mfma_f32_32x32x16_bf16 v[82:97], v[178:181], v[102:105], v[82:97]
	s_waitcnt lgkmcnt(1)
	v_mfma_f32_32x32x16_bf16 v[82:97], v[174:177], v[106:109], v[82:97]
	s_waitcnt lgkmcnt(0)
	v_mfma_f32_32x32x16_bf16 v[82:97], v[170:173], v[110:113], v[82:97]
	s_setprio 0
	s_mov_b64 s[2:3], -1
	s_cbranch_scc1 .LBB0_699
	v_mov_b32_e32 v195, v194
	s_nop 7
	v_pk_fma_f32 v[80:81], v[96:97], s[80:81], v[194:195] op_sel_hi:[1,0,1]
	v_pk_fma_f32 v[78:79], v[94:95], s[80:81], v[194:195] op_sel_hi:[1,0,1]
	v_pk_fma_f32 v[76:77], v[92:93], s[80:81], v[194:195] op_sel_hi:[1,0,1]
	v_pk_fma_f32 v[74:75], v[90:91], s[80:81], v[194:195] op_sel_hi:[1,0,1]
	v_pk_fma_f32 v[72:73], v[88:89], s[80:81], v[194:195] op_sel_hi:[1,0,1]
	v_pk_fma_f32 v[70:71], v[86:87], s[80:81], v[194:195] op_sel_hi:[1,0,1]
	v_pk_fma_f32 v[68:69], v[84:85], s[80:81], v[194:195] op_sel_hi:[1,0,1]
	v_pk_fma_f32 v[66:67], v[82:83], s[80:81], v[202:203] op_sel_hi:[1,0,1]
	s_mov_b64 s[2:3], 0

; #define LAS __attribute__((address_space(3)))
; __device__ __forceinline__ unsigned cvt_pk_bf16(float lo, float hi) { unsigned r; asm("v_cvt_pk_bf16_f32 %0, %1, %2" : "=v"(r) : "v"(lo), "v"(hi)); return r; }
; __device__ __forceinline__ int voff_band(int key, int d) { return ((key >> 3) * 2 + (d >> 5)) * 512 + (key & 7) * 64 + (d & 31) * 2; }
; __device__ __forceinline__ void attn_score(AttnState& st, bf16x8 (&pf)[2], const bf16x8 (&kf)[4], const bf16x8 (&qf)[4], int j, int qi, bool mask_hi,
;                                            LAS float* tab, float tconst, int lane) {
;     ...
;     float ps = 0.f;
; #pragma unroll
;     for (int e = 0; e < 16; ++e) { s[e] = __builtin_amdgcn_exp2f(s[e] - st.mrun); ps += s[e]; }
;     st.lsum += ps;
; #pragma unroll
;     for (int s2 = 0; s2 < 2; ++s2) { u32x4 w; w.x = cvt_pk_bf16(s[8 * s2 + 0], s[8 * s2 + 1]); w.y = cvt_pk_bf16(s[8 * s2 + 2], s[8 * s2 + 3]); w.z = cvt_pk_bf16(s[8 * s2 + 4], s[8 * s2 + 5]); w.w = cvt_pk_bf16(s[8 * s2 + 6], s[8 * s2 + 7]);
;         pf[s2] = __builtin_bit_cast(bf16x8, w); }
; __device__ __forceinline__ void band_attn_p2(const Params& P, int l, int b, int c, int h, LAS unsigned char* wl, int lane_) {
;     ...
;         for (int i = 0; i < 4; ++i) *(LAS bf16x8*)(vst + voff_band(vr0 + 8 * i, 8 * vch)) = vc[i];
.LBB0_709:
	v_add_f32_e32 v82, 0, v251
	v_add_f32_e32 v82, v252, v82
	v_add_f32_e32 v82, v228, v82
	v_add_f32_e32 v82, v211, v82
	v_add_f32_e32 v82, v221, v82
	v_add_f32_e32 v82, v222, v82
	v_add_f32_e32 v82, v223, v82
	v_add_f32_e32 v82, v224, v82
	v_add_f32_e32 v82, v225, v82
	v_add_f32_e32 v82, v226, v82
	v_add_f32_e32 v82, v227, v82
	v_add_f32_e32 v82, v217, v82
	v_sub_f32_e32 v66, v66, v0
	v_add_f32_e32 v82, v218, v82
	v_exp_f32_e32 v66, v66
	v_sub_f32_e32 v67, v67, v0
	v_add_f32_e32 v82, v219, v82
	v_exp_f32_e32 v67, v67
	v_sub_f32_e32 v68, v68, v0
	v_add_f32_e32 v82, v220, v82
	v_exp_f32_e32 v68, v68
	v_sub_f32_e32 v69, v69, v0
	v_add_f32_e32 v82, v216, v82
	v_exp_f32_e32 v69, v69
	v_sub_f32_e32 v70, v70, v0
	v_add_f32_e32 v229, v229, v82
	v_add_f32_e32 v82, 0, v66
	v_exp_f32_e32 v70, v70
	v_sub_f32_e32 v71, v71, v0
	v_add_f32_e32 v82, v67, v82
	v_exp_f32_e32 v71, v71
	v_sub_f32_e32 v72, v72, v0
	v_add_f32_e32 v82, v68, v82
	v_exp_f32_e32 v72, v72
	v_sub_f32_e32 v73, v73, v0
	v_add_f32_e32 v82, v69, v82
	v_exp_f32_e32 v73, v73
	v_sub_f32_e32 v74, v74, v0
	v_add_f32_e32 v82, v70, v82
	v_exp_f32_e32 v74, v74
	v_sub_f32_e32 v75, v75, v0
	v_add_f32_e32 v82, v71, v82
	v_exp_f32_e32 v75, v75
	v_sub_f32_e32 v76, v76, v0
	v_add_f32_e32 v82, v72, v82
	v_exp_f32_e32 v76, v76
	v_sub_f32_e32 v77, v77, v0
	v_add_f32_e32 v82, v73, v82
	v_exp_f32_e32 v77, v77
	v_sub_f32_e32 v78, v78, v0
	v_add_f32_e32 v82, v74, v82
	v_exp_f32_e32 v78, v78
	v_sub_f32_e32 v79, v79, v0
	v_add_f32_e32 v82, v75, v82
	v_exp_f32_e32 v79, v79
	v_sub_f32_e32 v80, v80, v0
	v_add_f32_e32 v82, v76, v82
	v_exp_f32_e32 v80, v80
	v_sub_f32_e32 v81, v81, v0
	v_add_f32_e32 v82, v77, v82
	v_exp_f32_e32 v81, v81
	s_cmpk_lg_i32 s7, 0xfde0
	s_cbranch_scc0 .Lp2_vwait0
	s_waitcnt vmcnt(4)
	s_branch .Lp2_vwait_done

; #define LAS __attribute__((address_space(3)))
; __device__ __forceinline__ int voff_band(int key, int d) { return ((key >> 3) * 2 + (d >> 5)) * 512 + (key & 7) * 64 + (d & 31) * 2; }
; __device__ __forceinline__ void band_attn_p2(const Params& P, int l, int b, int c, int h, LAS unsigned char* wl, int lane_) {
;     ...
;         for (int i = 0; i < 4; ++i) *(LAS bf16x8*)(vst + voff_band(vr0 + 8 * i, 8 * vch)) = vc[i];
;         const int trow = 4 * hi + ((lane & 15) >> 2), tcol = 16 * ((lane >> 4) & 1) + 4 * (lane & 3);
; #pragma unroll
;         for (int db = 0; db < 2; ++db)
; #pragma unroll
;             for (int s2 = 0; s2 < 2; ++s2) {
;                 const s16x4 a0 = tr_read(vst + voff_band(16 * s2 + trow, 32 * db + tcol));
;                 const s16x4 a1 = tr_read(vst + voff_band(16 * s2 + 8 + trow, 32 * db + tcol));
;                 const bf16x8 vf = (bf16x8){a0[0], a0[1], a0[2], a0[3], a1[0], a1[1], a1[2], a1[3]};
;                 __builtin_amdgcn_s_setprio(1);
; #pragma unroll
;                 for (int qb = 0; qb < 2; ++qb) st[qb].O[db] = __builtin_amdgcn_mfma_f32_32x32x16_bf16(vf, pf[qb][s2], st[qb].O[db], 0, 0, 0);
;                 __builtin_amdgcn_s_setprio(0);
;             }
; #pragma unroll
;         for (int i = 0; i < 4; ++i) kc[i] = kn[i];
.Lp2_vwait_done:
	ds_write_b128 v237, v[146:149] offset:2048
	ds_write_b128 v238, v[150:153] offset:2048
	ds_write_b128 v239, v[154:157] offset:2048
	ds_write_b128 v240, v[158:161] offset:2048
	v_add_f32_e32 v82, v78, v82
	v_cvt_pk_bf16_f32 v66, v66, v67
	v_cvt_pk_bf16_f32 v67, v68, v69
	v_cvt_pk_bf16_f32 v68, v70, v71
	v_cvt_pk_bf16_f32 v69, v72, v73
	ds_read_b64_tr_b16 v[70:71], v241 offset:2048
	ds_read_b64_tr_b16 v[72:73], v242 offset:2048
	v_add_f32_e32 v82, v79, v82
	v_add_f32_e32 v82, v80, v82
	v_add_f32_e32 v82, v81, v82
	s_add_i32 s0, s6, 1
	v_add_f32_e32 v207, v207, v82
	v_cvt_pk_bf16_f32 v74, v74, v75
	v_cvt_pk_bf16_f32 v75, v76, v77
	v_cvt_pk_bf16_f32 v76, v78, v79
	v_cvt_pk_bf16_f32 v77, v80, v81
	s_setprio 1
	s_waitcnt lgkmcnt(0)
	v_mfma_f32_32x32x16_bf16 v[50:65], v[70:73], v[166:169], v[50:65]
	v_mfma_f32_32x32x16_bf16 v[18:33], v[70:73], v[66:69], v[18:33]
	s_setprio 0
	ds_read_b64_tr_b16 v[70:71], v243 offset:2048
	ds_read_b64_tr_b16 v[72:73], v244 offset:2048
	s_setprio 1
	s_waitcnt lgkmcnt(0)
	v_mfma_f32_32x32x16_bf16 v[50:65], v[70:73], v[162:165], v[50:65]
	v_mfma_f32_32x32x16_bf16 v[18:33], v[70:73], v[74:77], v[18:33]
	s_setprio 0
	ds_read_b64_tr_b16 v[70:71], v245 offset:2048
	ds_read_b64_tr_b16 v[72:73], v246 offset:2048
	s_setprio 1
	s_waitcnt lgkmcnt(0)
	v_mfma_f32_32x32x16_bf16 v[34:49], v[70:73], v[166:169], v[34:49]
	v_mfma_f32_32x32x16_bf16 v[2:17], v[70:73], v[66:69], v[2:17]
	s_setprio 0
	ds_read_b64_tr_b16 v[66:67], v247 offset:2048
	ds_read_b64_tr_b16 v[68:69], v248 offset:2048
	s_setprio 1
	s_waitcnt lgkmcnt(0)
	v_mfma_f32_32x32x16_bf16 v[34:49], v[66:69], v[162:165], v[34:49]
	v_mfma_f32_32x32x16_bf16 v[2:17], v[66:69], v[74:77], v[2:17]
	s_setprio 0
	s_sub_i32 s7, s7, 32
	s_mov_b64 s[2:3], 0x28000
	s_cmp_gt_u32 s6, 16
	v_lshl_add_u64 v[204:205], v[204:205], 0, s[2:3]
	s_cbranch_scc1 .LBB0_711
	s_waitcnt vmcnt(0)
	v_mov_b64_e32 v[78:79], v[138:139]
	v_mov_b64_e32 v[74:75], v[142:143]
	v_mov_b64_e32 v[70:71], v[134:135]
	v_mov_b64_e32 v[66:67], v[130:131]
	v_mov_b64_e32 v[80:81], v[140:141]
	v_mov_b64_e32 v[76:77], v[144:145]
	v_mov_b64_e32 v[72:73], v[136:137]
	v_mov_b64_e32 v[68:69], v[132:133]
	s_mov_b32 s6, s0
	s_branch .LBB0_695

; __device__ __forceinline__ unsigned xb_add(unsigned* p, unsigned v) { return __hip_atomic_fetch_add(p, v, __ATOMIC_RELAXED, __HIP_MEMORY_SCOPE_AGENT); }
; __device__ __forceinline__ void xcd_barrier(const XcdBarrier& b) {
;     ...
;         unsigned nloc = b.st[0], nx = b.st[1];
;         if (nloc == 0u) { xcd_barrier_complete(bar, bx_, nloc, nx); b.st[0] = nloc; b.st[1] = nx; }
;         const unsigned old = xb_add(&bar[XB_XSUB(bx_)], 1u);
;         const unsigned gen = old / nloc;
;         if (old + 1u == (gen + 1u) * nloc) {
.LBB0_1282:
	s_lshl_b32 s20, s36, 6
	s_add_i32 s62, s20, 0x500
	s_lshl_b64 s[0:1], s[62:63], 2
	s_add_u32 s0, s34, s0
	s_addc_u32 s1, s35, s1
	v_mov_b64_e32 v[4:5], s[0:1]
	v_mov_b32_e32 v3, 1
	buffer_inv sc1
	flat_atomic_add v4, v[4:5], v3 sc0
	v_cvt_f32_u32_e32 v3, v2
	v_sub_u32_e32 v5, 0, v2
	v_rcp_iflag_f32_e32 v3, v3
	s_nop 0
	v_mul_f32_e32 v3, 0x4f7ffffe, v3
	v_cvt_u32_f32_e32 v3, v3
	v_mul_lo_u32 v5, v5, v3
	v_mul_hi_u32 v5, v3, v5
	v_add_u32_e32 v3, v3, v5
	s_waitcnt vmcnt(0) lgkmcnt(0)
	v_mul_hi_u32 v3, v4, v3
	v_mul_lo_u32 v5, v3, v2
	v_sub_u32_e32 v5, v4, v5
	v_cmp_ge_u32_e32 vcc, v5, v2
	v_add_u32_e32 v6, 1, v3
	s_nop 0
	v_cndmask_b32_e32 v3, v3, v6, vcc
	v_sub_u32_e32 v6, v5, v2
	v_cndmask_b32_e32 v5, v5, v6, vcc
	v_cmp_ge_u32_e32 vcc, v5, v2
	v_add_u32_e32 v5, 1, v3
	v_add_u32_e32 v6, 1, v4
	v_cndmask_b32_e32 v3, v3, v5, vcc
	v_mad_u64_u32 v[4:5], s[0:1], v2, v3, v[2:3]
	v_cmp_ne_u32_e32 vcc, v6, v4
	s_and_saveexec_b64 s[0:1], vcc
	s_xor_b64 s[0:1], exec, s[0:1]
	s_cbranch_execz .LBB0_1295
	s_add_i32 s62, s20, 0x900
	s_lshl_b64 s[2:3], s[62:63], 2
	s_add_u32 s4, s34, s2
	s_addc_u32 s5, s35, s3
	v_mov_b64_e32 v[4:5], s[4:5]
	flat_load_dword v0, v[4:5] sc1
	s_waitcnt vmcnt(0) lgkmcnt(0)
	v_cmp_eq_u32_e32 vcc, v0, v3
	s_and_saveexec_b64 s[2:3], vcc
	s_cbranch_execz .LBB0_1294
	s_mov_b32 s21, 1
	s_mov_b64 s[6:7], 0
	s_branch .LBB0_1286

; __device__ __forceinline__ unsigned xb_ld(unsigned* p)              { return __hip_atomic_load(p, __ATOMIC_RELAXED, __HIP_MEMORY_SCOPE_AGENT); }
; #define XB_SPIN(cond, bar) do { unsigned _sp = 0; while (cond) { __builtin_amdgcn_s_sleep(1); \
;     if ((++_sp & 255u) == 0u) { if (xb_ld(&(bar)[XB_TMO])) break; if (_sp > XB_SPIN_CAP) { atomicAdd(&(bar)[XB_TMO], 1u); break; } } } } while (0)
; __device__ __forceinline__ void xcd_barrier(const XcdBarrier& b) {
;     ...
;             XB_SPIN(xb_ld(&bar[XB_XGEN(bx_)]) == gen, bar);
;             __builtin_amdgcn_fence(__ATOMIC_ACQUIRE, "agent");
;             asm volatile("s_waitcnt vmcnt(0)" ::: "memory");
.LBB0_1294:
	s_or_b64 exec, exec, s[2:3]
	s_waitcnt vmcnt(0) lgkmcnt(0)
	s_waitcnt vmcnt(0)
